# RS4+prio: attention two wave groups one slot apart (waves 4-7 run the second half's P.V after the next tile barrier), barriers between slots, s_setprio 1 during scores+softmax, DMA issued inside P.V
# speedup vs baseline: 1.0171x; 1.0062x over previous
; #define Q5_MX(w) mx = fmaxf(mx, fmaxf(__builtin_fabsf(blo(w)), __builtin_fabsf(bhi(w))))
; #define Q5_Q2(w0, w1) q8p(blo(w0) * inv, bhi(w0) * inv, blo(w1) * inv, bhi(w1) * inv)
; __device__ __forceinline__ void attn_unit256q(const bf16* __restrict__ Qb, const unsigned char* __restrict__ Kc, const unsigned char* __restrict__ Kl, const float* __restrict__ Sc, const float* __restrict__ Sl, ...
;     ...
;   { const u32x4* Qw = (const u32x4*)(Qb + (size_t)(wid * 32 + r32) * 128 + hi * 16);
;     u32x4 qa[4], qb[4];
; #pragma unroll
;     for (int d0 = 0; d0 < 4; ++d0) { qa[d0] = Qw[d0 * 4]; qb[d0] = Qw[d0 * 4 + 1]; }
;     float mx = 0.f;
;     ...
; #pragma unroll
;     for (int d0 = 0; d0 < 4; ++d0) { Q5_MX(qa[d0].x); Q5_MX(qa[d0].y); Q5_MX(qa[d0].z); Q5_MX(qa[d0].w); Q5_MX(qb[d0].x); Q5_MX(qb[d0].y); Q5_MX(qb[d0].z); Q5_MX(qb[d0].w); }
;     ...
;     { auto rr = __builtin_amdgcn_permlane32_swap(__float_as_uint(mx), __float_as_uint(mx), false, false); mx = fmaxf(__uint_as_float(rr[0]), __uint_as_float(rr[1])); }
;     const float inv = mx > 0.f ? 127.f / mx : 0.f, qs = mx * (1.f / 127.f);
;     Cq = C * qs; thrq = mx > 0.f ? THR / (SCALE * qs) : 3.0e38f;
;     ...
; #pragma unroll
;     for (int d0 = 0; d0 < 4; ++d0) { qr[d0][0] = (int)Q5_Q2(qa[d0].x, qa[d0].y); qr[d0][1] = (int)Q5_Q2(qa[d0].z, qa[d0].w); qr[d0][2] = (int)Q5_Q2(qb[d0].x, qb[d0].y); qr[d0][3] = (int)Q5_Q2(qb[d0].z, qb[d0].w); }
.LBB0_537:
	s_or_b64 exec, exec, s[16:17]
	s_ashr_i32 s21, s20, 31
	s_ashr_i32 s3, s2, 31
	s_add_u32 s74, s18, s20
	s_addc_u32 s75, 0, s21
	s_lshl_b64 s[16:17], s[74:75], 7
	v_readlane_b32 s36, v243, 55
	v_readlane_b32 s37, v243, 56
	s_add_u32 s16, s36, s16
	s_addc_u32 s17, s37, s17
	s_add_u32 s76, s18, s2
	s_addc_u32 s77, 0, s3
	s_lshl_b64 s[18:19], s[76:77], 7
	s_add_u32 s72, s36, s18
	s_addc_u32 s73, s37, s19
	s_lshr_b64 s[18:19], s[74:75], 3
	s_add_u32 s18, s22, s18
	s_addc_u32 s19, s23, s19
	s_lshr_b64 s[74:75], s[76:77], 3
	s_add_u32 s74, s22, s74
	s_addc_u32 s75, s23, s75
	s_mul_i32 s76, s13, 0x880000
	s_add_u32 s76, s40, s76
	s_addc_u32 s77, s41, 0
	s_lshl_b64 s[20:21], s[20:21], 9
	s_add_u32 s20, s76, s20
	s_addc_u32 s21, s77, s21
	s_lshl_b64 s[2:3], s[2:3], 9
	v_bfe_u32 v71, v3, 3, 3
	s_add_u32 s76, s76, s2
	v_lshlrev_b32_e32 v72, 7, v71
	v_bitop3_b32 v71, v71, v3, 7 bitop3:0x78
	s_addc_u32 s77, s77, s3
	v_lshlrev_b32_e32 v71, 4, v71
	s_lshl_b32 s2, s4, 3
	v_lshrrev_b32_e32 v73, 2, v24
	s_lshl_b32 s80, s4, 10
	v_or_b32_e32 v73, s2, v73
	v_lshrrev_b32_e32 v74, 1, v24
	s_lshl_b32 s2, s4, 2
	v_or3_b32 v200, v71, v72, s80
	v_div_scale_f32 v71, s[84:85], v7, v7, s27
	v_and_b32_e32 v74, 8, v74
	s_and_b32 s2, s2, 4
	v_rcp_f32_e32 v72, v71
	v_and_b32_e32 v74, 32, v3
	v_lshlrev_b32_e32 v75, 3, v3
	v_and_or_b32 v74, v75, 24, v74
	v_lshlrev_b32_e32 v74, 1, v74
	v_lshl_or_b32 v204, v73, 9, v74
	v_fma_f32 v73, -v71, v72, 1.0
	v_fmac_f32_e32 v72, v73, v72
	v_div_scale_f32 v73, vcc, s27, v7, s27
	v_mul_f32_e32 v74, v73, v72
	v_fma_f32 v75, -v71, v74, v73
	v_fmac_f32_e32 v74, v75, v72
	v_fma_f32 v71, -v71, v74, v73
	v_div_fmas_f32 v71, v71, v72, v74
	v_div_fixup_f32 v7, v71, v7, s27
	v_cndmask_b32_e64 v71, 0, v7, s[0:1]
	v_mul_f32_e32 v7, v71, v25
	v_mul_f32_e32 v25, v71, v26
	v_mul_f32_e32 v26, v71, v27
	v_mul_f32_e32 v27, v71, v28
	v_rndne_f32_e32 v25, v25
	v_rndne_f32_e32 v7, v7
	v_cvt_i32_f32_e32 v25, v25
	v_rndne_f32_e32 v26, v26
	v_rndne_f32_e32 v27, v27
	v_cvt_i32_f32_e32 v7, v7
	v_cvt_i32_f32_sdwa v26, v26 dst_sel:WORD_1 dst_unused:UNUSED_PAD src0_sel:DWORD
	v_cvt_i32_f32_e32 v27, v27
	v_lshlrev_b32_e32 v25, 8, v25
	v_and_b32_e32 v25, 0xff00, v25
	v_and_b32_e32 v26, 0xff0000, v26
	v_perm_b32 v7, v27, v7, s34
	v_or3_b32 v164, v7, v25, v26
	v_mul_f32_e32 v25, v71, v30
	v_mul_f32_e32 v7, v71, v29
	v_mul_f32_e32 v26, v71, v31
	v_mul_f32_e32 v27, v71, v32
	v_rndne_f32_e32 v25, v25
	v_rndne_f32_e32 v7, v7
	v_cvt_i32_f32_e32 v25, v25
	v_rndne_f32_e32 v26, v26
	v_rndne_f32_e32 v27, v27
	v_cvt_i32_f32_e32 v7, v7
	v_cvt_i32_f32_sdwa v26, v26 dst_sel:WORD_1 dst_unused:UNUSED_PAD src0_sel:DWORD
	v_cvt_i32_f32_e32 v27, v27
	v_lshlrev_b32_e32 v25, 8, v25
	v_and_b32_e32 v25, 0xff00, v25
	v_and_b32_e32 v26, 0xff0000, v26
	v_perm_b32 v7, v27, v7, s34
	v_or3_b32 v165, v7, v25, v26
	v_mul_f32_e32 v25, v71, v34
	v_mul_f32_e32 v7, v71, v33
	v_mul_f32_e32 v26, v71, v35
	v_mul_f32_e32 v27, v71, v36
	v_rndne_f32_e32 v25, v25
	v_rndne_f32_e32 v7, v7
	v_cvt_i32_f32_e32 v25, v25
	v_rndne_f32_e32 v26, v26
	v_rndne_f32_e32 v27, v27
	v_cvt_i32_f32_e32 v7, v7
	v_cvt_i32_f32_sdwa v26, v26 dst_sel:WORD_1 dst_unused:UNUSED_PAD src0_sel:DWORD
	v_cvt_i32_f32_e32 v27, v27
	v_lshlrev_b32_e32 v25, 8, v25
	v_and_b32_e32 v25, 0xff00, v25
	v_and_b32_e32 v26, 0xff0000, v26
	v_perm_b32 v7, v27, v7, s34
	v_or3_b32 v166, v7, v25, v26
	v_mul_f32_e32 v25, v71, v38
	v_mul_f32_e32 v7, v71, v37
	v_mul_f32_e32 v26, v71, v39
	v_mul_f32_e32 v27, v71, v40
	v_rndne_f32_e32 v25, v25
	v_rndne_f32_e32 v7, v7
	v_cvt_i32_f32_e32 v25, v25
	v_rndne_f32_e32 v26, v26
	v_rndne_f32_e32 v27, v27
	v_cvt_i32_f32_e32 v7, v7
	v_cvt_i32_f32_sdwa v26, v26 dst_sel:WORD_1 dst_unused:UNUSED_PAD src0_sel:DWORD
	v_cvt_i32_f32_e32 v27, v27
	v_lshlrev_b32_e32 v25, 8, v25
	v_and_b32_e32 v25, 0xff00, v25
	v_and_b32_e32 v26, 0xff0000, v26
	v_perm_b32 v7, v27, v7, s34
	v_or3_b32 v167, v7, v25, v26
	v_mul_f32_e32 v25, v71, v42
	v_mul_f32_e32 v7, v71, v41
	v_mul_f32_e32 v26, v71, v43
	v_mul_f32_e32 v27, v71, v44
	v_rndne_f32_e32 v25, v25
	v_rndne_f32_e32 v7, v7
	v_cvt_i32_f32_e32 v25, v25
	v_rndne_f32_e32 v26, v26
	v_rndne_f32_e32 v27, v27
	v_cvt_i32_f32_e32 v7, v7
	v_cvt_i32_f32_sdwa v26, v26 dst_sel:WORD_1 dst_unused:UNUSED_PAD src0_sel:DWORD
	v_cvt_i32_f32_e32 v27, v27
	v_lshlrev_b32_e32 v25, 8, v25
	v_and_b32_e32 v25, 0xff00, v25
	v_and_b32_e32 v26, 0xff0000, v26
	v_perm_b32 v7, v27, v7, s34
	v_or3_b32 v168, v7, v25, v26
	v_mul_f32_e32 v25, v71, v46
	v_mul_f32_e32 v7, v71, v45
	v_mul_f32_e32 v26, v71, v47
	v_mul_f32_e32 v27, v71, v48
	v_rndne_f32_e32 v25, v25
	v_rndne_f32_e32 v7, v7
	v_cvt_i32_f32_e32 v25, v25
	v_rndne_f32_e32 v26, v26
	v_rndne_f32_e32 v27, v27
	v_cvt_i32_f32_e32 v7, v7
	v_cvt_i32_f32_sdwa v26, v26 dst_sel:WORD_1 dst_unused:UNUSED_PAD src0_sel:DWORD
	v_cvt_i32_f32_e32 v27, v27
	v_lshlrev_b32_e32 v25, 8, v25
	v_and_b32_e32 v25, 0xff00, v25
	v_and_b32_e32 v26, 0xff0000, v26
	v_perm_b32 v7, v27, v7, s34
	v_mul_f32_e32 v20, v71, v20
	v_or3_b32 v169, v7, v25, v26
	v_mul_f32_e32 v7, v71, v49
	v_mul_f32_e32 v25, v71, v68
	v_mul_f32_e32 v26, v71, v69
	v_rndne_f32_e32 v20, v20
	v_rndne_f32_e32 v7, v7
	v_cvt_i32_f32_e32 v20, v20
	v_rndne_f32_e32 v25, v25
	v_rndne_f32_e32 v26, v26
	v_cvt_i32_f32_e32 v7, v7
	v_cvt_i32_f32_sdwa v25, v25 dst_sel:WORD_1 dst_unused:UNUSED_PAD src0_sel:DWORD
	v_cvt_i32_f32_e32 v26, v26
	v_lshlrev_b32_e32 v20, 8, v20
	v_and_b32_e32 v20, 0xff00, v20
	v_and_b32_e32 v25, 0xff0000, v25
	v_perm_b32 v7, v26, v7, s34
	v_or3_b32 v170, v7, v20, v25
	v_mul_f32_e32 v20, v71, v65
	v_mul_f32_e32 v7, v71, v64
	v_mul_f32_e32 v25, v71, v66
	v_mul_f32_e32 v26, v71, v67
	v_rndne_f32_e32 v20, v20
; __device__ __forceinline__ int v_rd_base(int lane) { return ((lane & 3) << 3) | (((lane >> 2) & 3) << 6) | (((lane >> 4) & 1) << 5) | (((lane >> 5) & 1) << 8); }
; __device__ __forceinline__ int v_rd_base(int lane) { return ((lane & 3) << 3) | (((lane >> 2) & 3) << 6) | (((lane >> 4) & 1) << 5) | (((lane >> 5) & 1) << 8); }
; #define Q5_Q2(w0, w1) q8p(blo(w0) * inv, bhi(w0) * inv, blo(w1) * inv, bhi(w1) * inv)
; __device__ __forceinline__ void attn_unit256q(const bf16* __restrict__ Qb, const unsigned char* __restrict__ Kc, const unsigned char* __restrict__ Kl, const float* __restrict__ Sc, const float* __restrict__ Sl, ...
;     ...
;     const float inv = mx > 0.f ? 127.f / mx : 0.f, qs = mx * (1.f / 127.f);
;     Cq = C * qs; thrq = mx > 0.f ? THR / (SCALE * qs) : 3.0e38f;
;     ...
; #pragma unroll
;     for (int d0 = 0; d0 < 4; ++d0) { qr[d0][0] = (int)Q5_Q2(qa[d0].x, qa[d0].y); qr[d0][1] = (int)Q5_Q2(qa[d0].z, qa[d0].w); qr[d0][2] = (int)Q5_Q2(qb[d0].x, qb[d0].y); qr[d0][3] = (int)Q5_Q2(qb[d0].z, qb[d0].w); }
;     ...
;   }
;   { glds16((const char*)Kc + koff, (unsigned)__builtin_amdgcn_readfirstlane(kdst));
; #pragma unroll
;     for (int i = 0; i < 4; ++i) glds16((const char*)Vc + voff[i], (unsigned)__builtin_amdgcn_readfirstlane(vdst + i * 1024)); }
;   const int kx = (r32 & 7) << 4;
;   const lds_cptr kp0 = shm3 + LDS_K + r32 * 128, vp0 = shm3 + LDS_V + v_rd_base(lane);
;   float ksn0 = Sc[0], ksn1 = Sc[1];
	v_rndne_f32_e32 v7, v7
	v_cvt_i32_f32_e32 v20, v20
	v_rndne_f32_e32 v25, v25
	v_rndne_f32_e32 v26, v26
	v_cvt_i32_f32_e32 v7, v7
	v_cvt_i32_f32_sdwa v25, v25 dst_sel:WORD_1 dst_unused:UNUSED_PAD src0_sel:DWORD
	v_cvt_i32_f32_e32 v26, v26
	v_lshlrev_b32_e32 v20, 8, v20
	v_and_b32_e32 v20, 0xff00, v20
	v_and_b32_e32 v25, 0xff0000, v25
	v_perm_b32 v7, v26, v7, s34
	v_or3_b32 v171, v7, v20, v25
	v_mul_f32_e32 v20, v71, v61
	v_mul_f32_e32 v7, v71, v60
	v_mul_f32_e32 v25, v71, v62
	v_mul_f32_e32 v26, v71, v63
	v_rndne_f32_e32 v20, v20
	v_rndne_f32_e32 v7, v7
	v_cvt_i32_f32_e32 v20, v20
	v_rndne_f32_e32 v25, v25
	v_rndne_f32_e32 v26, v26
	v_cvt_i32_f32_e32 v7, v7
	v_cvt_i32_f32_sdwa v25, v25 dst_sel:WORD_1 dst_unused:UNUSED_PAD src0_sel:DWORD
	v_cvt_i32_f32_e32 v26, v26
	v_lshlrev_b32_e32 v20, 8, v20
	v_and_b32_e32 v20, 0xff00, v20
	v_and_b32_e32 v25, 0xff0000, v25
	v_perm_b32 v7, v26, v7, s34
	v_or3_b32 v172, v7, v20, v25
	v_mul_f32_e32 v20, v71, v57
	v_mul_f32_e32 v7, v71, v56
	v_mul_f32_e32 v25, v71, v58
	v_mul_f32_e32 v26, v71, v59
	v_rndne_f32_e32 v20, v20
	v_rndne_f32_e32 v7, v7
	v_cvt_i32_f32_e32 v20, v20
	v_rndne_f32_e32 v25, v25
	v_rndne_f32_e32 v26, v26
	v_cvt_i32_f32_e32 v7, v7
	v_cvt_i32_f32_sdwa v25, v25 dst_sel:WORD_1 dst_unused:UNUSED_PAD src0_sel:DWORD
	v_cvt_i32_f32_e32 v26, v26
	v_lshlrev_b32_e32 v20, 8, v20
	v_and_b32_e32 v20, 0xff00, v20
	v_and_b32_e32 v25, 0xff0000, v25
	v_perm_b32 v7, v26, v7, s34
	v_or3_b32 v173, v7, v20, v25
	v_mul_f32_e32 v20, v71, v53
	v_mul_f32_e32 v7, v71, v52
	v_mul_f32_e32 v25, v71, v54
	v_mul_f32_e32 v26, v71, v55
	v_rndne_f32_e32 v20, v20
	v_rndne_f32_e32 v7, v7
	v_cvt_i32_f32_e32 v20, v20
	v_rndne_f32_e32 v25, v25
	v_rndne_f32_e32 v26, v26
	v_cvt_i32_f32_e32 v7, v7
	v_cvt_i32_f32_sdwa v25, v25 dst_sel:WORD_1 dst_unused:UNUSED_PAD src0_sel:DWORD
	v_cvt_i32_f32_e32 v26, v26
	v_lshlrev_b32_e32 v20, 8, v20
	v_and_b32_e32 v20, 0xff00, v20
	v_and_b32_e32 v25, 0xff0000, v25
	v_perm_b32 v7, v26, v7, s34
	v_or3_b32 v174, v7, v20, v25
	v_mul_f32_e32 v20, v71, v23
	v_mul_f32_e32 v7, v71, v22
	v_mul_f32_e32 v22, v71, v50
	v_mul_f32_e32 v23, v71, v51
	v_rndne_f32_e32 v20, v20
	v_rndne_f32_e32 v7, v7
	v_cvt_i32_f32_e32 v20, v20
	v_rndne_f32_e32 v22, v22
	v_rndne_f32_e32 v23, v23
	v_cvt_i32_f32_e32 v7, v7
	v_cvt_i32_f32_sdwa v22, v22 dst_sel:WORD_1 dst_unused:UNUSED_PAD src0_sel:DWORD
	v_cvt_i32_f32_e32 v23, v23
	v_lshlrev_b32_e32 v20, 8, v20
	v_and_b32_e32 v20, 0xff00, v20
	v_and_b32_e32 v22, 0xff0000, v22
	v_perm_b32 v7, v23, v7, s34
	v_or3_b32 v175, v7, v20, v22
	v_mul_f32_e32 v7, v71, v17
	v_mul_f32_e32 v17, v71, v18
	v_mul_f32_e32 v18, v71, v19
	v_mul_f32_e32 v19, v71, v21
	v_rndne_f32_e32 v17, v17
	v_rndne_f32_e32 v7, v7
	v_cvt_i32_f32_e32 v17, v17
	v_rndne_f32_e32 v18, v18
	v_rndne_f32_e32 v19, v19
	v_cvt_i32_f32_e32 v7, v7
	v_cvt_i32_f32_sdwa v18, v18 dst_sel:WORD_1 dst_unused:UNUSED_PAD src0_sel:DWORD
	v_cvt_i32_f32_e32 v19, v19
	v_lshlrev_b32_e32 v17, 8, v17
	v_and_b32_e32 v17, 0xff00, v17
	v_and_b32_e32 v18, 0xff0000, v18
	v_perm_b32 v7, v19, v7, s34
	v_or3_b32 v176, v7, v17, v18
	v_mul_f32_e32 v7, v71, v13
	v_mul_f32_e32 v13, v71, v14
	v_mul_f32_e32 v14, v71, v15
	v_mul_f32_e32 v15, v71, v16
	v_rndne_f32_e32 v13, v13
	v_rndne_f32_e32 v7, v7
	v_cvt_i32_f32_e32 v13, v13
	v_rndne_f32_e32 v14, v14
	v_rndne_f32_e32 v15, v15
	v_cvt_i32_f32_e32 v7, v7
	v_cvt_i32_f32_sdwa v14, v14 dst_sel:WORD_1 dst_unused:UNUSED_PAD src0_sel:DWORD
	v_cvt_i32_f32_e32 v15, v15
	v_lshlrev_b32_e32 v13, 8, v13
	v_and_b32_e32 v13, 0xff00, v13
	v_and_b32_e32 v14, 0xff0000, v14
	v_perm_b32 v7, v15, v7, s34
	v_or3_b32 v177, v7, v13, v14
	v_mul_f32_e32 v7, v71, v9
	v_mul_f32_e32 v9, v71, v10
	v_mul_f32_e32 v10, v71, v11
	v_mul_f32_e32 v11, v71, v12
	v_rndne_f32_e32 v9, v9
	v_rndne_f32_e32 v7, v7
	v_cvt_i32_f32_e32 v9, v9
	v_rndne_f32_e32 v10, v10
	v_rndne_f32_e32 v11, v11
	v_cvt_i32_f32_e32 v7, v7
	v_cvt_i32_f32_sdwa v10, v10 dst_sel:WORD_1 dst_unused:UNUSED_PAD src0_sel:DWORD
	v_cvt_i32_f32_e32 v11, v11
	s_lshl_b32 s3, s4, 9
	s_lshl_b32 s81, s4, 12
	s_cmp_lg_u32 0, -1
	v_lshlrev_b32_e32 v9, 8, v9
	s_cselect_b32 s4, 0, 0
	v_and_b32_e32 v9, 0xff00, v9
	v_and_b32_e32 v10, 0xff0000, v10
	v_perm_b32 v7, v11, v7, s34
	s_add_i32 s2, s4, s81
	s_add_i32 s83, s80, s4
	v_or3_b32 v178, v7, v9, v10
	v_mul_f32_e32 v10, v71, v6
	v_lshl_add_u64 v[6:7], s[16:17], 0, v[200:201]
	s_mov_b32 s0, m0
	s_mov_b32 m0, s83
	s_nop 0
	global_load_lds_dwordx4 v[6:7], off
	s_mov_b32 m0, s0
	v_mov_b32_e32 v205, v201
	s_add_i32 s82, s2, 0x8000
	v_lshl_add_u64 v[6:7], s[20:21], 0, v[204:205]
	s_mov_b32 s0, m0
	s_mov_b32 m0, s82
	s_nop 0
	global_load_lds_dwordx4 v[6:7], off
	s_mov_b32 m0, s0
	v_mul_f32_e32 v11, v71, v8
	v_lshl_add_u64 v[8:9], v[6:7], 0, s[6:7]
	s_add_i32 s0, s2, 0x8400
	s_mov_b32 s1, m0
	s_mov_b32 m0, s0
	s_nop 0
	global_load_lds_dwordx4 v[8:9], off
	s_mov_b32 m0, s1
	v_lshl_add_u64 v[8:9], v[6:7], 0, s[8:9]
	s_add_i32 s0, s2, 0x8800
	s_mov_b32 s1, m0
	s_mov_b32 m0, s0
	s_nop 0
	global_load_lds_dwordx4 v[8:9], off
	s_mov_b32 m0, s1
	v_lshl_add_u64 v[6:7], v[6:7], 0, s[10:11]
	s_add_i32 s2, s2, 0x8c00
	s_mov_b32 s0, m0
	s_mov_b32 m0, s2
	s_nop 0
	global_load_lds_dwordx4 v[6:7], off
	s_mov_b32 m0, s0
	global_load_dwordx2 v[206:207], v201, s[18:19]
	v_mul_f32_e32 v5, v71, v5
	v_mul_f32_e32 v4, v71, v4
	v_rndne_f32_e32 v6, v10
	v_rndne_f32_e32 v5, v5
	v_cvt_i32_f32_e32 v6, v6
	v_rndne_f32_e32 v7, v11
	v_rndne_f32_e32 v4, v4
	v_cvt_i32_f32_e32 v5, v5
	v_cvt_i32_f32_sdwa v7, v7 dst_sel:WORD_1 dst_unused:UNUSED_PAD src0_sel:DWORD
	v_cvt_i32_f32_e32 v4, v4
	v_lshlrev_b32_e32 v6, 8, v6
	v_and_b32_e32 v219, 63, v3
	v_and_b32_e32 v6, 0xff00, v6
; __device__ __forceinline__ int v_rd_base(int lane) { return ((lane & 3) << 3) | (((lane >> 2) & 3) << 6) | (((lane >> 4) & 1) << 5) | (((lane >> 5) & 1) << 8); }
; __device__ __forceinline__ int v_rd_base(int lane) { return ((lane & 3) << 3) | (((lane >> 2) & 3) << 6) | (((lane >> 4) & 1) << 5) | (((lane >> 5) & 1) << 8); }
; __device__ __forceinline__ void attn_unit256q(const bf16* __restrict__ Qb, const unsigned char* __restrict__ Kc, const unsigned char* __restrict__ Kl, const float* __restrict__ Sc, const float* __restrict__ Sl, ...
;     ...
;   const int kx = (r32 & 7) << 4;
;   const lds_cptr kp0 = shm3 + LDS_K + r32 * 128, vp0 = shm3 + LDS_V + v_rd_base(lane);
;   float ksn0 = Sc[0], ksn1 = Sc[1];
;   constexpr float BIAS = 12582912.f;
;   i32x16 bini;
; #pragma unroll
;   for (int r = 0; r < 16; ++r) bini[r] = 0x4B400000;
;   asm volatile("" : "+v"(bini));
;   float m_reg = -1e30f, l_reg = 0.f, alpha = 1.f; f32x16 o[8];
; #pragma unroll
;   for (int d = 0; d < 8; ++d) o[d] = f32x16{};
;   f32x16 p; i32x16 p8; bf16x8 pa0, pa1; float ks0, ks1;
	v_and_b32_e32 v7, 0xff0000, v7
	v_perm_b32 v4, v4, v5, s34
	v_or3_b32 v179, v4, v6, v7
	v_lshlrev_b32_e32 v4, 3, v219
	v_lshlrev_b32_e32 v18, 4, v3
	v_and_b32_e32 v5, 24, v4
	v_and_b32_e32 v6, 0xc0, v18
	v_lshlrev_b32_e32 v3, 1, v3
	v_mov_b32_e32 v16, v2
	v_mov_b32_e32 v17, v2
	v_and_b32_e32 v19, 32, v3
	v_add3_u32 v20, 0, v5, v6
	v_and_b32_e32 v21, 0x100, v4
	v_mov_b32_e32 v3, v2
	v_mov_b32_e32 v4, v2
	v_mov_b32_e32 v5, v2
	v_mov_b32_e32 v6, v2
	v_mov_b32_e32 v7, v2
	v_mov_b32_e32 v8, v2
	v_mov_b32_e32 v9, v2
	v_mov_b32_e32 v10, v2
	v_mov_b32_e32 v11, v2
	v_mov_b32_e32 v12, v2
	v_mov_b32_e32 v13, v2
	v_mov_b32_e32 v14, v2
	v_mov_b32_e32 v15, v2
	v_mov_b64_e32 v[146:147], v[16:17]
	s_movk_i32 s0, 0x70
	s_add_i32 s78, s3, 0
	v_mov_b64_e32 v[144:145], v[14:15]
	v_mov_b64_e32 v[142:143], v[12:13]
	v_mov_b64_e32 v[140:141], v[10:11]
	v_mov_b64_e32 v[138:139], v[8:9]
	v_mov_b64_e32 v[136:137], v[6:7]
	v_mov_b64_e32 v[134:135], v[4:5]
	v_mov_b64_e32 v[132:133], v[2:3]
	v_add3_u32 v3, v20, v19, v21
	v_and_b32_e32 v4, 0x70, v18
	v_bitop3_b32 v21, v218, v18, s0 bitop3:0x78
	s_movk_i32 s0, 0x60
	s_add_i32 s78, s78, 0x20400
	v_lshl_add_u32 v20, v24, 7, 0
	v_bitop3_b32 v22, v218, v4, 32 bitop3:0x36
	v_bitop3_b32 v23, v218, v4, 64 bitop3:0x36
	v_bitop3_b32 v25, v218, v4, s0 bitop3:0x36
	v_mov_b32_e32 v18, v201
	v_mov_b32_e32 v19, v201
	v_mul_f32_e32 v221, 0x3e0293ee, v70
	v_lshl_add_u32 v223, v24, 2, s78
	v_mov_b32_e32 v4, v201
	v_mov_b32_e32 v5, v201
	v_mov_b32_e32 v6, v201
	v_mov_b32_e32 v7, v201
	v_mov_b32_e32 v8, v201
	v_mov_b32_e32 v9, v201
	v_mov_b32_e32 v10, v201
	v_mov_b32_e32 v11, v201
	v_mov_b32_e32 v12, v201
	v_mov_b32_e32 v13, v201
	v_mov_b32_e32 v14, v201
	v_mov_b32_e32 v15, v201
	v_mov_b32_e32 v16, v201
	v_mov_b32_e32 v17, v201
	v_add_u32_e32 v225, v20, v21
	v_add_u32_e32 v226, v20, v22
	v_add_u32_e32 v227, v20, v23
	v_add_u32_e32 v228, v20, v25
	v_mov_b64_e32 v[130:131], v[18:19]
	v_mov_b64_e32 v[114:115], v[18:19]
	v_mov_b64_e32 v[98:99], v[18:19]
	v_mov_b64_e32 v[82:83], v[18:19]
	v_mov_b64_e32 v[66:67], v[18:19]
	v_mov_b64_e32 v[50:51], v[18:19]
	v_mov_b64_e32 v[34:35], v[18:19]
	s_mov_b32 s79, 2
	v_add_u32_e32 v222, 0x8000, v3
	s_add_i32 s84, s70, -1
	v_cmp_gt_u32_e64 s[0:1], 32, v219
	v_mov_b32_e32 v224, 0
	v_mov_b32_e32 v237, 0xf149f2ca
	v_mul_f32_e32 v255, v221, v237
	v_mov_b64_e32 v[128:129], v[16:17]
	v_mov_b64_e32 v[126:127], v[14:15]
	v_mov_b64_e32 v[124:125], v[12:13]
	v_mov_b64_e32 v[122:123], v[10:11]
	v_mov_b64_e32 v[120:121], v[8:9]
	v_mov_b64_e32 v[118:119], v[6:7]
	v_mov_b64_e32 v[116:117], v[4:5]
	v_mov_b64_e32 v[112:113], v[16:17]
	v_mov_b64_e32 v[110:111], v[14:15]
	v_mov_b64_e32 v[108:109], v[12:13]
	v_mov_b64_e32 v[106:107], v[10:11]
	v_mov_b64_e32 v[104:105], v[8:9]
	v_mov_b64_e32 v[102:103], v[6:7]
	v_mov_b64_e32 v[100:101], v[4:5]
	v_mov_b64_e32 v[96:97], v[16:17]
	v_mov_b64_e32 v[94:95], v[14:15]
	v_mov_b64_e32 v[92:93], v[12:13]
	v_mov_b64_e32 v[90:91], v[10:11]
	v_mov_b64_e32 v[88:89], v[8:9]
	v_mov_b64_e32 v[86:87], v[6:7]
	v_mov_b64_e32 v[84:85], v[4:5]
	v_mov_b64_e32 v[80:81], v[16:17]
	v_mov_b64_e32 v[78:79], v[14:15]
	v_mov_b64_e32 v[76:77], v[12:13]
	v_mov_b64_e32 v[74:75], v[10:11]
	v_mov_b64_e32 v[72:73], v[8:9]
	v_mov_b64_e32 v[70:71], v[6:7]
	v_mov_b64_e32 v[68:69], v[4:5]
	v_mov_b64_e32 v[64:65], v[16:17]
	v_mov_b64_e32 v[62:63], v[14:15]
	v_mov_b64_e32 v[60:61], v[12:13]
	v_mov_b64_e32 v[58:59], v[10:11]
	v_mov_b64_e32 v[56:57], v[8:9]
	v_mov_b64_e32 v[54:55], v[6:7]
	v_mov_b64_e32 v[52:53], v[4:5]
	v_mov_b64_e32 v[48:49], v[16:17]
	v_mov_b64_e32 v[46:47], v[14:15]
	v_mov_b64_e32 v[44:45], v[12:13]
	v_mov_b64_e32 v[42:43], v[10:11]
	v_mov_b64_e32 v[40:41], v[8:9]
	v_mov_b64_e32 v[38:39], v[6:7]
	v_mov_b64_e32 v[36:37], v[4:5]
	v_mov_b64_e32 v[32:33], v[16:17]
	v_mov_b64_e32 v[30:31], v[14:15]
	v_mov_b64_e32 v[28:29], v[12:13]
	v_mov_b64_e32 v[26:27], v[10:11]
	v_mov_b64_e32 v[24:25], v[8:9]
	v_mov_b64_e32 v[22:23], v[6:7]
	v_mov_b64_e32 v[20:21], v[4:5]
	v_readlane_b32 s98, v243, 0
	s_nop 3
	s_cmp_ge_u32 s98, 4
	s_cbranch_scc1 .Lb4_entry
.LBB0_538:
	s_add_i32 s2, s79, -1
	s_min_u32 s85, s2, s84
	s_lshl_b32 s4, s85, 6
	s_cmp_lt_u32 s85, 4
	s_cselect_b64 s[2:3], -1, 0
	s_add_i32 s88, s4, 0xffffff00
	s_and_b64 s[86:87], s[2:3], exec
	s_cselect_b32 s4, s4, s88
	s_cselect_b32 s88, s17, s73
	s_cselect_b32 s89, s16, s72
	s_lshl_b64 s[86:87], s[4:5], 7
	s_add_u32 s86, s89, s86
	s_addc_u32 s87, s88, s87
	s_lshl_b32 s88, s85, 1
	s_mov_b32 s89, s5
	s_lshl_b64 s[88:89], s[88:89], 2
	s_add_u32 s85, s18, s88
	s_addc_u32 s90, s19, s89
	s_add_u32 s88, s74, s88
	s_addc_u32 s89, s75, s89
	s_add_u32 s88, s88, 0xffffffe0
	s_addc_u32 s89, s89, -1
	s_and_b64 s[2:3], s[2:3], exec
	s_cselect_b32 s3, s90, s89
	s_cselect_b32 s2, s85, s88
	s_waitcnt vmcnt(0) lgkmcnt(0)
	s_barrier
	s_setprio 1
	s_waitcnt vmcnt(0)
	global_load_dwordx2 v[208:209], v201, s[2:3]
	s_cselect_b32 s85, s21, s77
	s_cselect_b32 s88, s20, s76
	s_lshl_b64 s[2:3], s[4:5], 9
	s_add_u32 s2, s88, s2
	ds_read_b128 v[180:183], v225
	ds_read_b128 v[184:187], v226
	s_addc_u32 s3, s85, s3
	s_cmp_lg_u32 0, -1
	s_cselect_b32 s4, 0, 0
	s_add_i32 s85, s4, s80
	s_add_i32 s4, s4, s81
	s_addk_i32 s85, 0x4000
	s_add_i32 s88, s4, 0x10000
	s_waitcnt lgkmcnt(1)
	v_mfma_i32_32x32x32_i8 v[148:163], v[180:183], v[164:167], v[132:147]
	ds_read_b128 v[180:183], v227
	s_waitcnt lgkmcnt(1)
	v_mfma_i32_32x32x32_i8 v[148:163], v[184:187], v[168:171], v[148:163]
	ds_read_b128 v[188:191], v228
	s_waitcnt lgkmcnt(1)
	v_mfma_i32_32x32x32_i8 v[148:163], v[180:183], v[172:175], v[148:163]
	ds_read_b64_tr_b16 v[184:185], v3 offset:32768
	ds_read_b64_tr_b16 v[186:187], v3 offset:36864
	s_waitcnt lgkmcnt(2)
	v_mfma_i32_32x32x32_i8 v[148:163], v[188:191], v[176:179], v[148:163]
	ds_read_b64_tr_b16 v[180:181], v3 offset:33280
	ds_read_b64_tr_b16 v[182:183], v3 offset:37376
	s_nop 9
	v_max3_f32 v188, v148, v149, v150
	v_max3_f32 v189, v151, v152, v153
	v_max3_f32 v190, v154, v155, v156
	v_max3_f32 v191, v157, v158, v159
	v_max3_f32 v192, v160, v161, v162
	v_max3_f32 v188, v188, v189, v190
	v_max3_f32 v191, v191, v192, v163
	v_max_f32_e32 v188, v188, v191
	v_add_f32_e32 v188, 0xcb400000, v188
	v_fma_f32 v189, v206, v188, -v237
	v_cmp_gt_f32_e32 vcc, v189, v220
	s_cbranch_vccnz .Lv2_rare_h1
.Lv2_back_h1:
	v_mul_f32_e32 v189, v221, v206
	v_fma_f32 v190, s100, v189, v255
	v_fma_f32 v148, v148, v189, -v190
	v_fma_f32 v149, v149, v189, -v190
	v_exp_f32_e32 v148, v148
	v_fma_f32 v150, v150, v189, -v190
	v_exp_f32_e32 v149, v149
	v_fma_f32 v151, v151, v189, -v190
	v_exp_f32_e32 v150, v150
	v_fma_f32 v152, v152, v189, -v190
	v_exp_f32_e32 v151, v151
	v_fma_f32 v153, v153, v189, -v190
	v_exp_f32_e32 v152, v152
	v_fma_f32 v154, v154, v189, -v190
	v_exp_f32_e32 v153, v153
	v_fma_f32 v155, v155, v189, -v190
	v_exp_f32_e32 v154, v154
	v_fma_f32 v156, v156, v189, -v190
	v_exp_f32_e32 v155, v155
	v_fma_f32 v157, v157, v189, -v190
	v_exp_f32_e32 v156, v156
	v_fma_f32 v158, v158, v189, -v190
	v_exp_f32_e32 v157, v157
	v_fma_f32 v159, v159, v189, -v190
	v_exp_f32_e32 v158, v158
	v_fma_f32 v160, v160, v189, -v190
	v_exp_f32_e32 v159, v159
	v_fma_f32 v161, v161, v189, -v190
	v_exp_f32_e32 v160, v160
	v_fma_f32 v162, v162, v189, -v190
	v_exp_f32_e32 v161, v161
	v_fma_f32 v163, v163, v189, -v190
	v_exp_f32_e32 v162, v162
	v_exp_f32_e32 v163, v163
	v_add_f32_e32 v188, v148, v149
	v_add_f32_e32 v189, v150, v151
	v_add_f32_e32 v190, v152, v153
	v_add_f32_e32 v191, v154, v155
	v_add_f32_e32 v192, v156, v157
	v_add_f32_e32 v193, v158, v159
	v_add_f32_e32 v194, v160, v161
	v_add_f32_e32 v195, v162, v163
	v_add_f32_e32 v188, v188, v189
	v_add_f32_e32 v190, v190, v191
	v_add_f32_e32 v192, v192, v193
	v_add_f32_e32 v194, v194, v195
	v_add_f32_e32 v188, v188, v190
	v_add_f32_e32 v192, v192, v194
	v_add_f32_e32 v188, v188, v192
	v_add_f32_e32 v224, v224, v188
	v_cvt_pk_bf16_f32 v155, v154, v155
	v_cvt_pk_bf16_f32 v154, v152, v153
	v_cvt_pk_bf16_f32 v152, v148, v149
	v_cvt_pk_bf16_f32 v153, v150, v151
	v_cvt_pk_bf16_f32 v148, v156, v157
	v_cvt_pk_bf16_f32 v149, v158, v159
	v_cvt_pk_bf16_f32 v150, v160, v161
	v_cvt_pk_bf16_f32 v151, v162, v163
	s_barrier
	s_setprio 0
	s_waitcnt lgkmcnt(2)
	v_mfma_f32_32x32x16_bf16 v[4:19], v[152:155], v[184:187], v[4:19]
	ds_read_b64_tr_b16 v[156:157], v3 offset:33792
	ds_read_b64_tr_b16 v[158:159], v3 offset:37888
	s_waitcnt lgkmcnt(2)
	v_mfma_f32_32x32x16_bf16 v[116:131], v[152:155], v[180:183], v[116:131]
	ds_read_b64_tr_b16 v[160:161], v3 offset:34304
	ds_read_b64_tr_b16 v[162:163], v3 offset:38400
	s_add_i32 m0, s80, 0x4000
	s_nop 0
	global_load_lds_dwordx4 v200, s[86:87]
	s_waitcnt lgkmcnt(2)
	v_mfma_f32_32x32x16_bf16 v[100:115], v[152:155], v[156:159], v[100:115]
	ds_read_b64_tr_b16 v[156:157], v3 offset:34816
	ds_read_b64_tr_b16 v[158:159], v3 offset:38912
	s_waitcnt lgkmcnt(2)
	v_mfma_f32_32x32x16_bf16 v[84:99], v[152:155], v[160:163], v[84:99]
	ds_read_b64_tr_b16 v[160:161], v3 offset:35328
	ds_read_b64_tr_b16 v[162:163], v3 offset:39424
	s_add_i32 m0, s81, 0x10000
	s_nop 0
	global_load_lds_dwordx4 v204, s[2:3]
	s_waitcnt lgkmcnt(2)
	v_mfma_f32_32x32x16_bf16 v[68:83], v[152:155], v[156:159], v[68:83]
	ds_read_b64_tr_b16 v[156:157], v3 offset:35840
	ds_read_b64_tr_b16 v[158:159], v3 offset:39936
	s_waitcnt lgkmcnt(2)
	v_mfma_f32_32x32x16_bf16 v[52:67], v[152:155], v[160:163], v[52:67]
	ds_read_b64_tr_b16 v[160:161], v3 offset:36352
	ds_read_b64_tr_b16 v[162:163], v3 offset:40448
	s_add_u32 s2, s2, 0x80
	s_addc_u32 s3, s3, 0
	s_add_i32 m0, s81, 0x10400
	s_nop 0
	global_load_lds_dwordx4 v204, s[2:3]
	s_waitcnt lgkmcnt(2)
	v_mfma_f32_32x32x16_bf16 v[36:51], v[152:155], v[156:159], v[36:51]
	ds_read_b64_tr_b16 v[156:157], v3 offset:40960
	ds_read_b64_tr_b16 v[158:159], v3 offset:45056
	s_waitcnt lgkmcnt(2)
	v_mfma_f32_32x32x16_bf16 v[20:35], v[152:155], v[160:163], v[20:35]
	ds_read_b64_tr_b16 v[152:153], v3 offset:41472
	ds_read_b64_tr_b16 v[154:155], v3 offset:45568
	s_add_u32 s2, s2, 0x80
	s_addc_u32 s3, s3, 0
	s_add_i32 m0, s81, 0x10800
	s_nop 0
	global_load_lds_dwordx4 v204, s[2:3]
	s_waitcnt lgkmcnt(2)
	v_mfma_f32_32x32x16_bf16 v[4:19], v[148:151], v[156:159], v[4:19]
	ds_read_b64_tr_b16 v[156:157], v3 offset:41984
	ds_read_b64_tr_b16 v[158:159], v3 offset:46080
	s_waitcnt lgkmcnt(2)
	v_mfma_f32_32x32x16_bf16 v[116:131], v[148:151], v[152:155], v[116:131]
	ds_read_b64_tr_b16 v[152:153], v3 offset:42496
	ds_read_b64_tr_b16 v[154:155], v3 offset:46592
	s_add_u32 s2, s2, 0x80
	s_addc_u32 s3, s3, 0
	s_add_i32 m0, s81, 0x10c00
	s_nop 0
	global_load_lds_dwordx4 v204, s[2:3]
	s_waitcnt lgkmcnt(2)
	v_mfma_f32_32x32x16_bf16 v[100:115], v[148:151], v[156:159], v[100:115]
	ds_read_b64_tr_b16 v[156:157], v3 offset:43008
	ds_read_b64_tr_b16 v[158:159], v3 offset:47104
	s_waitcnt lgkmcnt(2)
	v_mfma_f32_32x32x16_bf16 v[84:99], v[148:151], v[152:155], v[84:99]
	ds_read_b64_tr_b16 v[152:153], v3 offset:43520
	ds_read_b64_tr_b16 v[154:155], v3 offset:47616
	s_waitcnt lgkmcnt(2)
	v_mfma_f32_32x32x16_bf16 v[68:83], v[148:151], v[156:159], v[68:83]
	ds_read_b64_tr_b16 v[156:157], v3 offset:44032
	ds_read_b64_tr_b16 v[158:159], v3 offset:48128
	s_waitcnt lgkmcnt(2)
	v_mfma_f32_32x32x16_bf16 v[52:67], v[148:151], v[152:155], v[52:67]
	ds_read_b64_tr_b16 v[152:153], v3 offset:44544
	ds_read_b64_tr_b16 v[154:155], v3 offset:48640
	s_waitcnt lgkmcnt(2)
	v_mfma_f32_32x32x16_bf16 v[36:51], v[148:151], v[156:159], v[36:51]
	s_waitcnt lgkmcnt(0)
	v_mfma_f32_32x32x16_bf16 v[20:35], v[148:151], v[152:155], v[20:35]
	s_barrier
	s_setprio 1
	ds_read_b128 v[180:183], v225 offset:4096
	ds_read_b128 v[184:187], v226 offset:4096
	s_waitcnt lgkmcnt(1)
	v_mfma_i32_32x32x32_i8 v[148:163], v[180:183], v[164:167], v[132:147]
	ds_read_b128 v[180:183], v227 offset:4096
	s_waitcnt lgkmcnt(1)
	v_mfma_i32_32x32x32_i8 v[148:163], v[184:187], v[168:171], v[148:163]
	ds_read_b128 v[188:191], v228 offset:4096
	s_waitcnt lgkmcnt(1)
	v_mfma_i32_32x32x32_i8 v[148:163], v[180:183], v[172:175], v[148:163]
	ds_read_b64_tr_b16 v[184:185], v3 offset:49152
	ds_read_b64_tr_b16 v[186:187], v3 offset:53248
	s_waitcnt lgkmcnt(2)
	v_mfma_i32_32x32x32_i8 v[148:163], v[188:191], v[176:179], v[148:163]
	ds_read_b64_tr_b16 v[180:181], v3 offset:49664
	ds_read_b64_tr_b16 v[182:183], v3 offset:53760
	s_nop 9
	v_max3_f32 v188, v148, v149, v150
	v_max3_f32 v189, v151, v152, v153
	v_max3_f32 v190, v154, v155, v156
	v_max3_f32 v191, v157, v158, v159
	v_max3_f32 v192, v160, v161, v162
	v_max3_f32 v188, v188, v189, v190
	v_max3_f32 v191, v191, v192, v163
	v_max_f32_e32 v188, v188, v191
	v_add_f32_e32 v188, 0xcb400000, v188
	v_fma_f32 v189, v207, v188, -v237
	v_cmp_gt_f32_e32 vcc, v189, v220
	s_cbranch_vccnz .Lv2_rare_h2
.Lv2_back_h2:
	v_mul_f32_e32 v189, v221, v207
	v_fma_f32 v190, s100, v189, v255
	v_fma_f32 v148, v148, v189, -v190
	v_fma_f32 v149, v149, v189, -v190
	v_exp_f32_e32 v148, v148
	v_fma_f32 v150, v150, v189, -v190
	v_exp_f32_e32 v149, v149
	v_fma_f32 v151, v151, v189, -v190
	v_exp_f32_e32 v150, v150
	v_fma_f32 v152, v152, v189, -v190
	v_exp_f32_e32 v151, v151
	v_fma_f32 v153, v153, v189, -v190
	v_exp_f32_e32 v152, v152
	v_fma_f32 v154, v154, v189, -v190
	v_exp_f32_e32 v153, v153
	v_fma_f32 v155, v155, v189, -v190
	v_exp_f32_e32 v154, v154
	v_fma_f32 v156, v156, v189, -v190
	v_exp_f32_e32 v155, v155
	v_fma_f32 v157, v157, v189, -v190
	v_exp_f32_e32 v156, v156
	v_fma_f32 v158, v158, v189, -v190
	v_exp_f32_e32 v157, v157
	v_fma_f32 v159, v159, v189, -v190
	v_exp_f32_e32 v158, v158
	v_fma_f32 v160, v160, v189, -v190
	v_exp_f32_e32 v159, v159
	v_fma_f32 v161, v161, v189, -v190
	v_exp_f32_e32 v160, v160
	v_fma_f32 v162, v162, v189, -v190
	v_exp_f32_e32 v161, v161
	v_fma_f32 v163, v163, v189, -v190
	v_exp_f32_e32 v162, v162
	v_exp_f32_e32 v163, v163
	v_add_f32_e32 v188, v148, v149
	v_add_f32_e32 v189, v150, v151
	v_add_f32_e32 v190, v152, v153
	v_add_f32_e32 v191, v154, v155
	v_add_f32_e32 v192, v156, v157
	v_add_f32_e32 v193, v158, v159
	v_add_f32_e32 v194, v160, v161
	v_add_f32_e32 v195, v162, v163
	v_add_f32_e32 v188, v188, v189
	v_add_f32_e32 v190, v190, v191
	v_add_f32_e32 v192, v192, v193
	v_add_f32_e32 v194, v194, v195
	v_add_f32_e32 v188, v188, v190
	v_add_f32_e32 v192, v192, v194
	v_add_f32_e32 v188, v188, v192
	v_add_f32_e32 v224, v224, v188
	v_cvt_pk_bf16_f32 v155, v154, v155
	v_cvt_pk_bf16_f32 v154, v152, v153
	v_cvt_pk_bf16_f32 v152, v148, v149
	v_cvt_pk_bf16_f32 v153, v150, v151
	v_cvt_pk_bf16_f32 v148, v156, v157
	v_cvt_pk_bf16_f32 v149, v158, v159
	v_cvt_pk_bf16_f32 v150, v160, v161
	v_cvt_pk_bf16_f32 v151, v162, v163
	s_barrier
	s_setprio 0
	s_waitcnt lgkmcnt(2)
	v_mfma_f32_32x32x16_bf16 v[4:19], v[152:155], v[184:187], v[4:19]
	ds_read_b64_tr_b16 v[156:157], v3 offset:50176
	ds_read_b64_tr_b16 v[158:159], v3 offset:54272
	s_waitcnt lgkmcnt(2)
	v_mfma_f32_32x32x16_bf16 v[116:131], v[152:155], v[180:183], v[116:131]
	ds_read_b64_tr_b16 v[160:161], v3 offset:50688
	ds_read_b64_tr_b16 v[162:163], v3 offset:54784
	s_waitcnt lgkmcnt(2)
	v_mfma_f32_32x32x16_bf16 v[100:115], v[152:155], v[156:159], v[100:115]
	ds_read_b64_tr_b16 v[156:157], v3 offset:51200
	ds_read_b64_tr_b16 v[158:159], v3 offset:55296
	s_waitcnt lgkmcnt(2)
	v_mfma_f32_32x32x16_bf16 v[84:99], v[152:155], v[160:163], v[84:99]
	ds_read_b64_tr_b16 v[160:161], v3 offset:51712
	ds_read_b64_tr_b16 v[162:163], v3 offset:55808
	s_waitcnt lgkmcnt(2)
	v_mfma_f32_32x32x16_bf16 v[68:83], v[152:155], v[156:159], v[68:83]
	ds_read_b64_tr_b16 v[156:157], v3 offset:52224
	ds_read_b64_tr_b16 v[158:159], v3 offset:56320
	s_waitcnt lgkmcnt(2)
	v_mfma_f32_32x32x16_bf16 v[52:67], v[152:155], v[160:163], v[52:67]
	ds_read_b64_tr_b16 v[160:161], v3 offset:52736
	ds_read_b64_tr_b16 v[162:163], v3 offset:56832
	s_waitcnt lgkmcnt(2)
	v_mfma_f32_32x32x16_bf16 v[36:51], v[152:155], v[156:159], v[36:51]
	ds_read_b64_tr_b16 v[156:157], v3 offset:57344
	ds_read_b64_tr_b16 v[158:159], v3 offset:61440
	s_waitcnt lgkmcnt(2)
	v_mfma_f32_32x32x16_bf16 v[20:35], v[152:155], v[160:163], v[20:35]
	ds_read_b64_tr_b16 v[152:153], v3 offset:57856
	ds_read_b64_tr_b16 v[154:155], v3 offset:61952
	s_waitcnt lgkmcnt(2)
	v_mfma_f32_32x32x16_bf16 v[4:19], v[148:151], v[156:159], v[4:19]
	ds_read_b64_tr_b16 v[156:157], v3 offset:58368
	ds_read_b64_tr_b16 v[158:159], v3 offset:62464
	s_waitcnt lgkmcnt(2)
	v_mfma_f32_32x32x16_bf16 v[116:131], v[148:151], v[152:155], v[116:131]
	ds_read_b64_tr_b16 v[152:153], v3 offset:58880
	ds_read_b64_tr_b16 v[154:155], v3 offset:62976
	s_waitcnt lgkmcnt(2)
	v_mfma_f32_32x32x16_bf16 v[100:115], v[148:151], v[156:159], v[100:115]
	ds_read_b64_tr_b16 v[156:157], v3 offset:59392
	ds_read_b64_tr_b16 v[158:159], v3 offset:63488
	s_waitcnt lgkmcnt(2)
	v_mfma_f32_32x32x16_bf16 v[84:99], v[148:151], v[152:155], v[84:99]
	ds_read_b64_tr_b16 v[152:153], v3 offset:59904
	ds_read_b64_tr_b16 v[154:155], v3 offset:64000
	s_waitcnt lgkmcnt(2)
	v_mfma_f32_32x32x16_bf16 v[68:83], v[148:151], v[156:159], v[68:83]
	ds_read_b64_tr_b16 v[156:157], v3 offset:60416
	ds_read_b64_tr_b16 v[158:159], v3 offset:64512
	s_waitcnt lgkmcnt(2)
	v_mfma_f32_32x32x16_bf16 v[52:67], v[148:151], v[152:155], v[52:67]
	ds_read_b64_tr_b16 v[152:153], v3 offset:60928
	ds_read_b64_tr_b16 v[154:155], v3 offset:65024
	s_waitcnt lgkmcnt(2)
	v_mfma_f32_32x32x16_bf16 v[36:51], v[148:151], v[156:159], v[36:51]
	s_waitcnt lgkmcnt(0)
	v_mfma_f32_32x32x16_bf16 v[20:35], v[148:151], v[152:155], v[20:35]
	s_min_u32 s85, s79, s84
	s_lshl_b32 s4, s85, 6
	s_cmp_lt_u32 s85, 4
	s_cselect_b64 s[2:3], -1, 0
	s_add_i32 s88, s4, 0xffffff00
	s_and_b64 s[86:87], s[2:3], exec
	s_cselect_b32 s4, s4, s88
	s_cselect_b32 s88, s17, s73
	s_cselect_b32 s89, s16, s72
	s_lshl_b64 s[86:87], s[4:5], 7
	s_add_u32 s86, s89, s86
	s_addc_u32 s87, s88, s87
	s_lshl_b32 s88, s85, 1
	s_mov_b32 s89, s5
	s_lshl_b64 s[88:89], s[88:89], 2
	s_add_u32 s85, s18, s88
	s_addc_u32 s90, s19, s89
	s_add_u32 s88, s74, s88
	s_addc_u32 s89, s75, s89
	s_add_u32 s88, s88, 0xffffffe0
	s_addc_u32 s89, s89, -1
	s_and_b64 s[2:3], s[2:3], exec
	s_waitcnt vmcnt(0)
	v_mov_b32_e32 v236, v209
	s_cselect_b32 s3, s90, s89
	s_cselect_b32 s2, s85, s88
	s_waitcnt vmcnt(0) lgkmcnt(0)
	s_barrier
	s_setprio 1
	global_load_dwordx2 v[206:207], v201, s[2:3]
	ds_read_b128 v[180:183], v225 offset:16384
	ds_read_b128 v[184:187], v226 offset:16384
	s_cselect_b32 s85, s21, s77
	s_cselect_b32 s88, s20, s76
	s_lshl_b64 s[2:3], s[4:5], 9
	s_add_u32 s2, s88, s2
	s_addc_u32 s3, s85, s3
	s_waitcnt lgkmcnt(1)
	v_mfma_i32_32x32x32_i8 v[148:163], v[180:183], v[164:167], v[132:147]
	ds_read_b128 v[180:183], v227 offset:16384
	s_waitcnt lgkmcnt(1)
	v_mfma_i32_32x32x32_i8 v[148:163], v[184:187], v[168:171], v[148:163]
	ds_read_b128 v[188:191], v228 offset:16384
	s_waitcnt lgkmcnt(1)
	v_mfma_i32_32x32x32_i8 v[148:163], v[180:183], v[172:175], v[148:163]
	ds_read_b64_tr_b16 v[184:185], v222 offset:32768
	ds_read_b64_tr_b16 v[186:187], v222 offset:36864
	s_waitcnt lgkmcnt(2)
	v_mfma_i32_32x32x32_i8 v[148:163], v[188:191], v[176:179], v[148:163]
	ds_read_b64_tr_b16 v[180:181], v222 offset:33280
	ds_read_b64_tr_b16 v[182:183], v222 offset:37376
	s_nop 9
	s_mov_b32 s90, s94
	v_max3_f32 v188, v148, v149, v150
	v_max3_f32 v189, v151, v152, v153
	v_max3_f32 v190, v154, v155, v156
	v_max3_f32 v191, v157, v158, v159
	v_max3_f32 v192, v160, v161, v162
	v_max3_f32 v188, v188, v189, v190
	v_max3_f32 v191, v191, v192, v163
	v_max_f32_e32 v188, v188, v191
	v_add_f32_e32 v188, 0xcb400000, v188
	v_fma_f32 v189, v208, v188, -v237
	v_cmp_gt_f32_e32 vcc, v189, v220
	s_cbranch_vccnz .Lv2_rare_h3
.Lv2_back_h3:
	v_mul_f32_e32 v189, v221, v208
	v_fma_f32 v190, s100, v189, v255
	v_fma_f32 v148, v148, v189, -v190
	v_fma_f32 v149, v149, v189, -v190
	v_exp_f32_e32 v148, v148
	v_fma_f32 v150, v150, v189, -v190
	v_exp_f32_e32 v149, v149
	v_fma_f32 v151, v151, v189, -v190
	v_exp_f32_e32 v150, v150
	v_fma_f32 v152, v152, v189, -v190
	v_exp_f32_e32 v151, v151
	v_fma_f32 v153, v153, v189, -v190
	v_exp_f32_e32 v152, v152
	v_fma_f32 v154, v154, v189, -v190
	v_exp_f32_e32 v153, v153
	v_fma_f32 v155, v155, v189, -v190
	v_exp_f32_e32 v154, v154
	v_fma_f32 v156, v156, v189, -v190
	v_exp_f32_e32 v155, v155
	v_fma_f32 v157, v157, v189, -v190
	v_exp_f32_e32 v156, v156
	v_fma_f32 v158, v158, v189, -v190
	v_exp_f32_e32 v157, v157
	v_fma_f32 v159, v159, v189, -v190
	v_exp_f32_e32 v158, v158
	v_fma_f32 v160, v160, v189, -v190
	v_exp_f32_e32 v159, v159
	v_fma_f32 v161, v161, v189, -v190
	v_exp_f32_e32 v160, v160
	v_fma_f32 v162, v162, v189, -v190
	v_exp_f32_e32 v161, v161
	v_fma_f32 v163, v163, v189, -v190
	v_exp_f32_e32 v162, v162
	v_exp_f32_e32 v163, v163
	v_add_f32_e32 v188, v148, v149
	v_add_f32_e32 v189, v150, v151
	v_add_f32_e32 v190, v152, v153
	v_add_f32_e32 v191, v154, v155
	v_add_f32_e32 v192, v156, v157
	v_add_f32_e32 v193, v158, v159
	v_add_f32_e32 v194, v160, v161
	v_add_f32_e32 v195, v162, v163
	v_add_f32_e32 v188, v188, v189
	v_add_f32_e32 v190, v190, v191
	v_add_f32_e32 v192, v192, v193
	v_add_f32_e32 v194, v194, v195
	v_add_f32_e32 v188, v188, v190
	v_add_f32_e32 v192, v192, v194
	v_add_f32_e32 v188, v188, v192
	v_add_f32_e32 v224, v224, v188
	v_cvt_pk_bf16_f32 v155, v154, v155
	v_cvt_pk_bf16_f32 v154, v152, v153
	v_cvt_pk_bf16_f32 v152, v148, v149
	v_cvt_pk_bf16_f32 v153, v150, v151
	v_cvt_pk_bf16_f32 v148, v156, v157
	v_cvt_pk_bf16_f32 v149, v158, v159
	v_cvt_pk_bf16_f32 v150, v160, v161
	v_cvt_pk_bf16_f32 v151, v162, v163
	s_barrier
	s_setprio 0
	s_waitcnt lgkmcnt(2)
	v_mfma_f32_32x32x16_bf16 v[4:19], v[152:155], v[184:187], v[4:19]
	ds_read_b64_tr_b16 v[156:157], v222 offset:33792
	ds_read_b64_tr_b16 v[158:159], v222 offset:37888
	s_waitcnt lgkmcnt(2)
	v_mfma_f32_32x32x16_bf16 v[116:131], v[152:155], v[180:183], v[116:131]
	ds_read_b64_tr_b16 v[160:161], v222 offset:34304
	ds_read_b64_tr_b16 v[162:163], v222 offset:38400
	s_add_i32 m0, s83, 0
	s_nop 0
	global_load_lds_dwordx4 v200, s[86:87]
	s_waitcnt lgkmcnt(2)
	v_mfma_f32_32x32x16_bf16 v[100:115], v[152:155], v[156:159], v[100:115]
	ds_read_b64_tr_b16 v[156:157], v222 offset:34816
	ds_read_b64_tr_b16 v[158:159], v222 offset:38912
	s_waitcnt lgkmcnt(2)
	v_mfma_f32_32x32x16_bf16 v[84:99], v[152:155], v[160:163], v[84:99]
	ds_read_b64_tr_b16 v[160:161], v222 offset:35328
	ds_read_b64_tr_b16 v[162:163], v222 offset:39424
	s_add_i32 m0, s82, 0
	s_nop 0
	global_load_lds_dwordx4 v204, s[2:3]
	s_waitcnt lgkmcnt(2)
	v_mfma_f32_32x32x16_bf16 v[68:83], v[152:155], v[156:159], v[68:83]
	ds_read_b64_tr_b16 v[156:157], v222 offset:35840
	ds_read_b64_tr_b16 v[158:159], v222 offset:39936
	s_waitcnt lgkmcnt(2)
	v_mfma_f32_32x32x16_bf16 v[52:67], v[152:155], v[160:163], v[52:67]
	ds_read_b64_tr_b16 v[160:161], v222 offset:36352
	ds_read_b64_tr_b16 v[162:163], v222 offset:40448
	s_add_u32 s2, s2, 0x80
	s_addc_u32 s3, s3, 0
	s_add_i32 m0, s82, 0x400
	s_nop 0
	global_load_lds_dwordx4 v204, s[2:3]
	s_waitcnt lgkmcnt(2)
	v_mfma_f32_32x32x16_bf16 v[36:51], v[152:155], v[156:159], v[36:51]
	ds_read_b64_tr_b16 v[156:157], v222 offset:40960
	ds_read_b64_tr_b16 v[158:159], v222 offset:45056
	s_waitcnt lgkmcnt(2)
	v_mfma_f32_32x32x16_bf16 v[20:35], v[152:155], v[160:163], v[20:35]
	ds_read_b64_tr_b16 v[152:153], v222 offset:41472
	ds_read_b64_tr_b16 v[154:155], v222 offset:45568
	s_add_u32 s2, s2, 0x80
	s_addc_u32 s3, s3, 0
	s_add_i32 m0, s82, 0x800
	s_nop 0
	global_load_lds_dwordx4 v204, s[2:3]
	s_waitcnt lgkmcnt(2)
	v_mfma_f32_32x32x16_bf16 v[4:19], v[148:151], v[156:159], v[4:19]
	ds_read_b64_tr_b16 v[156:157], v222 offset:41984
	ds_read_b64_tr_b16 v[158:159], v222 offset:46080
	s_waitcnt lgkmcnt(2)
	v_mfma_f32_32x32x16_bf16 v[116:131], v[148:151], v[152:155], v[116:131]
	ds_read_b64_tr_b16 v[152:153], v222 offset:42496
	ds_read_b64_tr_b16 v[154:155], v222 offset:46592
	s_add_u32 s2, s2, 0x80
	s_addc_u32 s3, s3, 0
	s_add_i32 m0, s82, 0xc00
	s_nop 0
	global_load_lds_dwordx4 v204, s[2:3]
	s_waitcnt lgkmcnt(2)
	v_mfma_f32_32x32x16_bf16 v[100:115], v[148:151], v[156:159], v[100:115]
	ds_read_b64_tr_b16 v[156:157], v222 offset:43008
	ds_read_b64_tr_b16 v[158:159], v222 offset:47104
	s_waitcnt lgkmcnt(2)
	v_mfma_f32_32x32x16_bf16 v[84:99], v[148:151], v[152:155], v[84:99]
	ds_read_b64_tr_b16 v[152:153], v222 offset:43520
	ds_read_b64_tr_b16 v[154:155], v222 offset:47616
	s_waitcnt lgkmcnt(2)
	v_mfma_f32_32x32x16_bf16 v[68:83], v[148:151], v[156:159], v[68:83]
	ds_read_b64_tr_b16 v[156:157], v222 offset:44032
	ds_read_b64_tr_b16 v[158:159], v222 offset:48128
	s_waitcnt lgkmcnt(2)
	v_mfma_f32_32x32x16_bf16 v[52:67], v[148:151], v[152:155], v[52:67]
	ds_read_b64_tr_b16 v[152:153], v222 offset:44544
	ds_read_b64_tr_b16 v[154:155], v222 offset:48640
	s_waitcnt lgkmcnt(2)
	v_mfma_f32_32x32x16_bf16 v[36:51], v[148:151], v[156:159], v[36:51]
	s_waitcnt lgkmcnt(0)
	v_mfma_f32_32x32x16_bf16 v[20:35], v[148:151], v[152:155], v[20:35]
	s_barrier
	s_setprio 1
	ds_read_b128 v[180:183], v225 offset:20480
	ds_read_b128 v[184:187], v226 offset:20480
	s_waitcnt lgkmcnt(1)
	v_mfma_i32_32x32x32_i8 v[148:163], v[180:183], v[164:167], v[132:147]
	ds_read_b128 v[180:183], v227 offset:20480
	s_waitcnt lgkmcnt(1)
	v_mfma_i32_32x32x32_i8 v[148:163], v[184:187], v[168:171], v[148:163]
	ds_read_b128 v[188:191], v228 offset:20480
	s_waitcnt lgkmcnt(1)
	v_mfma_i32_32x32x32_i8 v[148:163], v[180:183], v[172:175], v[148:163]
	ds_read_b64_tr_b16 v[184:185], v222 offset:49152
	ds_read_b64_tr_b16 v[186:187], v222 offset:53248
	s_waitcnt lgkmcnt(2)
	v_mfma_i32_32x32x32_i8 v[148:163], v[188:191], v[176:179], v[148:163]
	ds_read_b64_tr_b16 v[180:181], v222 offset:49664
	ds_read_b64_tr_b16 v[182:183], v222 offset:53760
	s_nop 9
	v_max3_f32 v188, v148, v149, v150
	v_max3_f32 v189, v151, v152, v153
	v_max3_f32 v190, v154, v155, v156
	v_max3_f32 v191, v157, v158, v159
	v_max3_f32 v192, v160, v161, v162
	v_max3_f32 v188, v188, v189, v190
	v_max3_f32 v191, v191, v192, v163
	v_max_f32_e32 v188, v188, v191
	v_add_f32_e32 v188, 0xcb400000, v188
	v_fma_f32 v189, v236, v188, -v237
	v_cmp_gt_f32_e32 vcc, v189, v220
	s_cbranch_vccnz .Lv2_rare_h4
; __device__ __forceinline__ void attn_unit256q(const bf16* __restrict__ Qb, const unsigned char* __restrict__ Kc, const unsigned char* __restrict__ Kl, const float* __restrict__ Sc, const float* __restrict__ Sl, ...
;     ...
;   for (int j = 0; j < NT; j += 2) {
;     A5_TILE(0, 0, KBUF, VBUF, j);
;     A5_TILE(KBUF, VBUF, 0, 0, j + 1);
;   }
.Lv2_back_h4:
	v_mul_f32_e32 v189, v221, v236
	v_fma_f32 v190, s100, v189, v255
	v_fma_f32 v148, v148, v189, -v190
	v_fma_f32 v149, v149, v189, -v190
	v_exp_f32_e32 v148, v148
	v_fma_f32 v150, v150, v189, -v190
	v_exp_f32_e32 v149, v149
	v_fma_f32 v151, v151, v189, -v190
	v_exp_f32_e32 v150, v150
	v_fma_f32 v152, v152, v189, -v190
	v_exp_f32_e32 v151, v151
	v_fma_f32 v153, v153, v189, -v190
	v_exp_f32_e32 v152, v152
	v_fma_f32 v154, v154, v189, -v190
	v_exp_f32_e32 v153, v153
	v_fma_f32 v155, v155, v189, -v190
	v_exp_f32_e32 v154, v154
	v_fma_f32 v156, v156, v189, -v190
	v_exp_f32_e32 v155, v155
	v_fma_f32 v157, v157, v189, -v190
	v_exp_f32_e32 v156, v156
	v_fma_f32 v158, v158, v189, -v190
	v_exp_f32_e32 v157, v157
	v_fma_f32 v159, v159, v189, -v190
	v_exp_f32_e32 v158, v158
	v_fma_f32 v160, v160, v189, -v190
	v_exp_f32_e32 v159, v159
	v_fma_f32 v161, v161, v189, -v190
	v_exp_f32_e32 v160, v160
	v_fma_f32 v162, v162, v189, -v190
	v_exp_f32_e32 v161, v161
	v_fma_f32 v163, v163, v189, -v190
	v_exp_f32_e32 v162, v162
	v_exp_f32_e32 v163, v163
	v_add_f32_e32 v188, v148, v149
	v_add_f32_e32 v189, v150, v151
	v_add_f32_e32 v190, v152, v153
	v_add_f32_e32 v191, v154, v155
	v_add_f32_e32 v192, v156, v157
	v_add_f32_e32 v193, v158, v159
	v_add_f32_e32 v194, v160, v161
	v_add_f32_e32 v195, v162, v163
	v_add_f32_e32 v188, v188, v189
	v_add_f32_e32 v190, v190, v191
	v_add_f32_e32 v192, v192, v193
	v_add_f32_e32 v194, v194, v195
	v_add_f32_e32 v188, v188, v190
	v_add_f32_e32 v192, v192, v194
	v_add_f32_e32 v188, v188, v192
	v_add_f32_e32 v224, v224, v188
	v_cvt_pk_bf16_f32 v155, v154, v155
	v_cvt_pk_bf16_f32 v154, v152, v153
	v_cvt_pk_bf16_f32 v152, v148, v149
	v_cvt_pk_bf16_f32 v153, v150, v151
	v_cvt_pk_bf16_f32 v148, v156, v157
	v_cvt_pk_bf16_f32 v149, v158, v159
	v_cvt_pk_bf16_f32 v150, v160, v161
	v_cvt_pk_bf16_f32 v151, v162, v163
	s_barrier
	s_setprio 0
	s_waitcnt lgkmcnt(2)
	v_mfma_f32_32x32x16_bf16 v[4:19], v[152:155], v[184:187], v[4:19]
	ds_read_b64_tr_b16 v[156:157], v222 offset:50176
	ds_read_b64_tr_b16 v[158:159], v222 offset:54272
	s_waitcnt lgkmcnt(2)
	v_mfma_f32_32x32x16_bf16 v[116:131], v[152:155], v[180:183], v[116:131]
	ds_read_b64_tr_b16 v[160:161], v222 offset:50688
	ds_read_b64_tr_b16 v[162:163], v222 offset:54784
	s_waitcnt lgkmcnt(2)
	v_mfma_f32_32x32x16_bf16 v[100:115], v[152:155], v[156:159], v[100:115]
	ds_read_b64_tr_b16 v[156:157], v222 offset:51200
	ds_read_b64_tr_b16 v[158:159], v222 offset:55296
	s_waitcnt lgkmcnt(2)
	v_mfma_f32_32x32x16_bf16 v[84:99], v[152:155], v[160:163], v[84:99]
	ds_read_b64_tr_b16 v[160:161], v222 offset:51712
	ds_read_b64_tr_b16 v[162:163], v222 offset:55808
	s_waitcnt lgkmcnt(2)
	v_mfma_f32_32x32x16_bf16 v[68:83], v[152:155], v[156:159], v[68:83]
	ds_read_b64_tr_b16 v[156:157], v222 offset:52224
	ds_read_b64_tr_b16 v[158:159], v222 offset:56320
	s_waitcnt lgkmcnt(2)
	v_mfma_f32_32x32x16_bf16 v[52:67], v[152:155], v[160:163], v[52:67]
	ds_read_b64_tr_b16 v[160:161], v222 offset:52736
	ds_read_b64_tr_b16 v[162:163], v222 offset:56832
	s_waitcnt lgkmcnt(2)
	v_mfma_f32_32x32x16_bf16 v[36:51], v[152:155], v[156:159], v[36:51]
	ds_read_b64_tr_b16 v[156:157], v222 offset:57344
	ds_read_b64_tr_b16 v[158:159], v222 offset:61440
	s_waitcnt lgkmcnt(2)
	v_mfma_f32_32x32x16_bf16 v[20:35], v[152:155], v[160:163], v[20:35]
	ds_read_b64_tr_b16 v[152:153], v222 offset:57856
	ds_read_b64_tr_b16 v[154:155], v222 offset:61952
	s_waitcnt lgkmcnt(2)
	v_mfma_f32_32x32x16_bf16 v[4:19], v[148:151], v[156:159], v[4:19]
	ds_read_b64_tr_b16 v[156:157], v222 offset:58368
	ds_read_b64_tr_b16 v[158:159], v222 offset:62464
	s_waitcnt lgkmcnt(2)
	v_mfma_f32_32x32x16_bf16 v[116:131], v[148:151], v[152:155], v[116:131]
	ds_read_b64_tr_b16 v[152:153], v222 offset:58880
	ds_read_b64_tr_b16 v[154:155], v222 offset:62976
	s_waitcnt lgkmcnt(2)
	v_mfma_f32_32x32x16_bf16 v[100:115], v[148:151], v[156:159], v[100:115]
	ds_read_b64_tr_b16 v[156:157], v222 offset:59392
	ds_read_b64_tr_b16 v[158:159], v222 offset:63488
	s_waitcnt lgkmcnt(2)
	v_mfma_f32_32x32x16_bf16 v[84:99], v[148:151], v[152:155], v[84:99]
	ds_read_b64_tr_b16 v[152:153], v222 offset:59904
	ds_read_b64_tr_b16 v[154:155], v222 offset:64000
	s_waitcnt lgkmcnt(2)
	v_mfma_f32_32x32x16_bf16 v[68:83], v[148:151], v[156:159], v[68:83]
	ds_read_b64_tr_b16 v[156:157], v222 offset:60416
	ds_read_b64_tr_b16 v[158:159], v222 offset:64512
	s_waitcnt lgkmcnt(2)
	v_mfma_f32_32x32x16_bf16 v[52:67], v[148:151], v[152:155], v[52:67]
	ds_read_b64_tr_b16 v[152:153], v222 offset:60928
	ds_read_b64_tr_b16 v[154:155], v222 offset:65024
	s_waitcnt lgkmcnt(2)
	v_mfma_f32_32x32x16_bf16 v[36:51], v[148:151], v[156:159], v[36:51]
	s_waitcnt lgkmcnt(0)
	v_mfma_f32_32x32x16_bf16 v[20:35], v[148:151], v[152:155], v[20:35]
	s_add_i32 s2, s79, 2
	s_cmp_ge_u32 s79, s70
	s_cbranch_scc1 .LBB0_557
	s_mov_b32 s79, s2
	s_branch .LBB0_538
.Lv2_rare_h1:
	v_mov_b32_e32 v189, v188
	s_nop 1
	v_permlane32_swap_b32_e32 v188, v189
	v_max_f32_e32 v188, v188, v189
	v_mul_f32_e32 v189, v206, v188
	v_fma_f32 v188, v206, v188, -v237
	v_max_f32_e32 v189, v237, v189
	v_cmp_gt_f32_e32 vcc, v188, v220
	s_nop 1
	v_cndmask_b32_e32 v189, v237, v189, vcc
	v_sub_f32_e32 v188, v237, v189
	v_mul_f32_e32 v188, v221, v188
	v_exp_f32_e32 v254, v188
	v_mov_b32_e32 v237, v189
	v_mul_f32_e32 v255, v221, v189
	v_mul_f32_e32 v224, v224, v254
	s_and_saveexec_b64 vcc, s[0:1]
	ds_write_b32 v223, v254
	s_or_b64 exec, exec, vcc
	s_waitcnt lgkmcnt(0)
	v_add_u32_e32 v253, s78, v218
	ds_read_b128 v[244:247], v253 offset:96
	ds_read_b128 v[248:251], v253 offset:64
	s_waitcnt lgkmcnt(1)
	v_pk_mul_f32 v[16:17], v[16:17], v[244:245]
	v_pk_mul_f32 v[18:19], v[18:19], v[246:247]
	v_pk_mul_f32 v[128:129], v[128:129], v[244:245]
	v_pk_mul_f32 v[130:131], v[130:131], v[246:247]
	v_pk_mul_f32 v[112:113], v[112:113], v[244:245]
	v_pk_mul_f32 v[114:115], v[114:115], v[246:247]
	v_pk_mul_f32 v[96:97], v[96:97], v[244:245]
	v_pk_mul_f32 v[98:99], v[98:99], v[246:247]
	v_pk_mul_f32 v[80:81], v[80:81], v[244:245]
	v_pk_mul_f32 v[82:83], v[82:83], v[246:247]
	v_pk_mul_f32 v[64:65], v[64:65], v[244:245]
	v_pk_mul_f32 v[66:67], v[66:67], v[246:247]
	v_pk_mul_f32 v[48:49], v[48:49], v[244:245]
	v_pk_mul_f32 v[50:51], v[50:51], v[246:247]
	v_pk_mul_f32 v[32:33], v[32:33], v[244:245]
	v_pk_mul_f32 v[34:35], v[34:35], v[246:247]
	s_waitcnt lgkmcnt(0)
	v_pk_mul_f32 v[12:13], v[12:13], v[248:249]
	v_pk_mul_f32 v[14:15], v[14:15], v[250:251]
	v_pk_mul_f32 v[124:125], v[124:125], v[248:249]
	v_pk_mul_f32 v[126:127], v[126:127], v[250:251]
	v_pk_mul_f32 v[108:109], v[108:109], v[248:249]
	v_pk_mul_f32 v[110:111], v[110:111], v[250:251]
	v_pk_mul_f32 v[92:93], v[92:93], v[248:249]
	v_pk_mul_f32 v[94:95], v[94:95], v[250:251]
	v_pk_mul_f32 v[76:77], v[76:77], v[248:249]
	v_pk_mul_f32 v[78:79], v[78:79], v[250:251]
	v_pk_mul_f32 v[60:61], v[60:61], v[248:249]
	v_pk_mul_f32 v[62:63], v[62:63], v[250:251]
	v_pk_mul_f32 v[44:45], v[44:45], v[248:249]
	v_pk_mul_f32 v[46:47], v[46:47], v[250:251]
	v_pk_mul_f32 v[28:29], v[28:29], v[248:249]
	v_pk_mul_f32 v[30:31], v[30:31], v[250:251]
	ds_read_b128 v[244:247], v253 offset:32
	ds_read_b128 v[248:251], v253
	s_waitcnt lgkmcnt(1)
	v_pk_mul_f32 v[8:9], v[8:9], v[244:245]
	v_pk_mul_f32 v[10:11], v[10:11], v[246:247]
	v_pk_mul_f32 v[120:121], v[120:121], v[244:245]
	v_pk_mul_f32 v[122:123], v[122:123], v[246:247]
	v_pk_mul_f32 v[104:105], v[104:105], v[244:245]
	v_pk_mul_f32 v[106:107], v[106:107], v[246:247]
	v_pk_mul_f32 v[88:89], v[88:89], v[244:245]
	v_pk_mul_f32 v[90:91], v[90:91], v[246:247]
	v_pk_mul_f32 v[72:73], v[72:73], v[244:245]
	v_pk_mul_f32 v[74:75], v[74:75], v[246:247]
	v_pk_mul_f32 v[56:57], v[56:57], v[244:245]
	v_pk_mul_f32 v[58:59], v[58:59], v[246:247]
	v_pk_mul_f32 v[40:41], v[40:41], v[244:245]
	v_pk_mul_f32 v[42:43], v[42:43], v[246:247]
	v_pk_mul_f32 v[24:25], v[24:25], v[244:245]
	v_pk_mul_f32 v[26:27], v[26:27], v[246:247]
	s_waitcnt lgkmcnt(0)
	v_pk_mul_f32 v[4:5], v[4:5], v[248:249]
	v_pk_mul_f32 v[6:7], v[6:7], v[250:251]
	v_pk_mul_f32 v[116:117], v[116:117], v[248:249]
	v_pk_mul_f32 v[118:119], v[118:119], v[250:251]
	v_pk_mul_f32 v[100:101], v[100:101], v[248:249]
	v_pk_mul_f32 v[102:103], v[102:103], v[250:251]
	v_pk_mul_f32 v[84:85], v[84:85], v[248:249]
	v_pk_mul_f32 v[86:87], v[86:87], v[250:251]
	v_pk_mul_f32 v[68:69], v[68:69], v[248:249]
	v_pk_mul_f32 v[70:71], v[70:71], v[250:251]
	v_pk_mul_f32 v[52:53], v[52:53], v[248:249]
	v_pk_mul_f32 v[54:55], v[54:55], v[250:251]
	v_pk_mul_f32 v[36:37], v[36:37], v[248:249]
	v_pk_mul_f32 v[38:39], v[38:39], v[250:251]
	v_pk_mul_f32 v[20:21], v[20:21], v[248:249]
	v_pk_mul_f32 v[22:23], v[22:23], v[250:251]
	s_branch .Lv2_back_h1
.Lv2_rare_h2:
	v_mov_b32_e32 v189, v188
	s_nop 1
	v_permlane32_swap_b32_e32 v188, v189
	v_max_f32_e32 v188, v188, v189
	v_mul_f32_e32 v189, v207, v188
	v_fma_f32 v188, v207, v188, -v237
	v_max_f32_e32 v189, v237, v189
	v_cmp_gt_f32_e32 vcc, v188, v220
	s_nop 1
	v_cndmask_b32_e32 v189, v237, v189, vcc
	v_sub_f32_e32 v188, v237, v189
	v_mul_f32_e32 v188, v221, v188
	v_exp_f32_e32 v254, v188
	v_mov_b32_e32 v237, v189
	v_mul_f32_e32 v255, v221, v189
	v_mul_f32_e32 v224, v224, v254
	s_and_saveexec_b64 vcc, s[0:1]
	ds_write_b32 v223, v254
	s_or_b64 exec, exec, vcc
	s_waitcnt lgkmcnt(0)
	v_add_u32_e32 v253, s78, v218
	ds_read_b128 v[244:247], v253 offset:96
	ds_read_b128 v[248:251], v253 offset:64
	s_waitcnt lgkmcnt(1)
	v_pk_mul_f32 v[16:17], v[16:17], v[244:245]
	v_pk_mul_f32 v[18:19], v[18:19], v[246:247]
	v_pk_mul_f32 v[128:129], v[128:129], v[244:245]
	v_pk_mul_f32 v[130:131], v[130:131], v[246:247]
	v_pk_mul_f32 v[112:113], v[112:113], v[244:245]
	v_pk_mul_f32 v[114:115], v[114:115], v[246:247]
	v_pk_mul_f32 v[96:97], v[96:97], v[244:245]
	v_pk_mul_f32 v[98:99], v[98:99], v[246:247]
	v_pk_mul_f32 v[80:81], v[80:81], v[244:245]
	v_pk_mul_f32 v[82:83], v[82:83], v[246:247]
	v_pk_mul_f32 v[64:65], v[64:65], v[244:245]
	v_pk_mul_f32 v[66:67], v[66:67], v[246:247]
	v_pk_mul_f32 v[48:49], v[48:49], v[244:245]
	v_pk_mul_f32 v[50:51], v[50:51], v[246:247]
	v_pk_mul_f32 v[32:33], v[32:33], v[244:245]
	v_pk_mul_f32 v[34:35], v[34:35], v[246:247]
	s_waitcnt lgkmcnt(0)
	v_pk_mul_f32 v[12:13], v[12:13], v[248:249]
	v_pk_mul_f32 v[14:15], v[14:15], v[250:251]
	v_pk_mul_f32 v[124:125], v[124:125], v[248:249]
	v_pk_mul_f32 v[126:127], v[126:127], v[250:251]
	v_pk_mul_f32 v[108:109], v[108:109], v[248:249]
	v_pk_mul_f32 v[110:111], v[110:111], v[250:251]
	v_pk_mul_f32 v[92:93], v[92:93], v[248:249]
	v_pk_mul_f32 v[94:95], v[94:95], v[250:251]
	v_pk_mul_f32 v[76:77], v[76:77], v[248:249]
	v_pk_mul_f32 v[78:79], v[78:79], v[250:251]
	v_pk_mul_f32 v[60:61], v[60:61], v[248:249]
	v_pk_mul_f32 v[62:63], v[62:63], v[250:251]
	v_pk_mul_f32 v[44:45], v[44:45], v[248:249]
	v_pk_mul_f32 v[46:47], v[46:47], v[250:251]
	v_pk_mul_f32 v[28:29], v[28:29], v[248:249]
	v_pk_mul_f32 v[30:31], v[30:31], v[250:251]
	ds_read_b128 v[244:247], v253 offset:32
	ds_read_b128 v[248:251], v253
	s_waitcnt lgkmcnt(1)
	v_pk_mul_f32 v[8:9], v[8:9], v[244:245]
	v_pk_mul_f32 v[10:11], v[10:11], v[246:247]
	v_pk_mul_f32 v[120:121], v[120:121], v[244:245]
	v_pk_mul_f32 v[122:123], v[122:123], v[246:247]
	v_pk_mul_f32 v[104:105], v[104:105], v[244:245]
	v_pk_mul_f32 v[106:107], v[106:107], v[246:247]
	v_pk_mul_f32 v[88:89], v[88:89], v[244:245]
	v_pk_mul_f32 v[90:91], v[90:91], v[246:247]
	v_pk_mul_f32 v[72:73], v[72:73], v[244:245]
	v_pk_mul_f32 v[74:75], v[74:75], v[246:247]
	v_pk_mul_f32 v[56:57], v[56:57], v[244:245]
	v_pk_mul_f32 v[58:59], v[58:59], v[246:247]
	v_pk_mul_f32 v[40:41], v[40:41], v[244:245]
	v_pk_mul_f32 v[42:43], v[42:43], v[246:247]
	v_pk_mul_f32 v[24:25], v[24:25], v[244:245]
	v_pk_mul_f32 v[26:27], v[26:27], v[246:247]
	s_waitcnt lgkmcnt(0)
	v_pk_mul_f32 v[4:5], v[4:5], v[248:249]
	v_pk_mul_f32 v[6:7], v[6:7], v[250:251]
	v_pk_mul_f32 v[116:117], v[116:117], v[248:249]
	v_pk_mul_f32 v[118:119], v[118:119], v[250:251]
	v_pk_mul_f32 v[100:101], v[100:101], v[248:249]
	v_pk_mul_f32 v[102:103], v[102:103], v[250:251]
	v_pk_mul_f32 v[84:85], v[84:85], v[248:249]
	v_pk_mul_f32 v[86:87], v[86:87], v[250:251]
	v_pk_mul_f32 v[68:69], v[68:69], v[248:249]
	v_pk_mul_f32 v[70:71], v[70:71], v[250:251]
	v_pk_mul_f32 v[52:53], v[52:53], v[248:249]
	v_pk_mul_f32 v[54:55], v[54:55], v[250:251]
	v_pk_mul_f32 v[36:37], v[36:37], v[248:249]
	v_pk_mul_f32 v[38:39], v[38:39], v[250:251]
	v_pk_mul_f32 v[20:21], v[20:21], v[248:249]
	v_pk_mul_f32 v[22:23], v[22:23], v[250:251]
	s_branch .Lv2_back_h2
.Lv2_rare_h3:
	v_mov_b32_e32 v189, v188
	s_nop 1
	v_permlane32_swap_b32_e32 v188, v189
	v_max_f32_e32 v188, v188, v189
	v_mul_f32_e32 v189, v208, v188
	v_fma_f32 v188, v208, v188, -v237
	v_max_f32_e32 v189, v237, v189
	v_cmp_gt_f32_e32 vcc, v188, v220
	s_nop 1
	v_cndmask_b32_e32 v189, v237, v189, vcc
	v_sub_f32_e32 v188, v237, v189
	v_mul_f32_e32 v188, v221, v188
	v_exp_f32_e32 v254, v188
	v_mov_b32_e32 v237, v189
	v_mul_f32_e32 v255, v221, v189
	v_mul_f32_e32 v224, v224, v254
	s_and_saveexec_b64 vcc, s[0:1]
	ds_write_b32 v223, v254
	s_or_b64 exec, exec, vcc
	s_waitcnt lgkmcnt(0)
	v_add_u32_e32 v253, s78, v218
	ds_read_b128 v[244:247], v253 offset:96
	ds_read_b128 v[248:251], v253 offset:64
	s_waitcnt lgkmcnt(1)
	v_pk_mul_f32 v[16:17], v[16:17], v[244:245]
	v_pk_mul_f32 v[18:19], v[18:19], v[246:247]
	v_pk_mul_f32 v[128:129], v[128:129], v[244:245]
	v_pk_mul_f32 v[130:131], v[130:131], v[246:247]
	v_pk_mul_f32 v[112:113], v[112:113], v[244:245]
	v_pk_mul_f32 v[114:115], v[114:115], v[246:247]
	v_pk_mul_f32 v[96:97], v[96:97], v[244:245]
	v_pk_mul_f32 v[98:99], v[98:99], v[246:247]
	v_pk_mul_f32 v[80:81], v[80:81], v[244:245]
	v_pk_mul_f32 v[82:83], v[82:83], v[246:247]
	v_pk_mul_f32 v[64:65], v[64:65], v[244:245]
	v_pk_mul_f32 v[66:67], v[66:67], v[246:247]
	v_pk_mul_f32 v[48:49], v[48:49], v[244:245]
	v_pk_mul_f32 v[50:51], v[50:51], v[246:247]
	v_pk_mul_f32 v[32:33], v[32:33], v[244:245]
	v_pk_mul_f32 v[34:35], v[34:35], v[246:247]
	s_waitcnt lgkmcnt(0)
	v_pk_mul_f32 v[12:13], v[12:13], v[248:249]
	v_pk_mul_f32 v[14:15], v[14:15], v[250:251]
	v_pk_mul_f32 v[124:125], v[124:125], v[248:249]
	v_pk_mul_f32 v[126:127], v[126:127], v[250:251]
	v_pk_mul_f32 v[108:109], v[108:109], v[248:249]
	v_pk_mul_f32 v[110:111], v[110:111], v[250:251]
	v_pk_mul_f32 v[92:93], v[92:93], v[248:249]
	v_pk_mul_f32 v[94:95], v[94:95], v[250:251]
	v_pk_mul_f32 v[76:77], v[76:77], v[248:249]
	v_pk_mul_f32 v[78:79], v[78:79], v[250:251]
	v_pk_mul_f32 v[60:61], v[60:61], v[248:249]
	v_pk_mul_f32 v[62:63], v[62:63], v[250:251]
	v_pk_mul_f32 v[44:45], v[44:45], v[248:249]
	v_pk_mul_f32 v[46:47], v[46:47], v[250:251]
	v_pk_mul_f32 v[28:29], v[28:29], v[248:249]
	v_pk_mul_f32 v[30:31], v[30:31], v[250:251]
	ds_read_b128 v[244:247], v253 offset:32
	ds_read_b128 v[248:251], v253
	s_waitcnt lgkmcnt(1)
	v_pk_mul_f32 v[8:9], v[8:9], v[244:245]
	v_pk_mul_f32 v[10:11], v[10:11], v[246:247]
	v_pk_mul_f32 v[120:121], v[120:121], v[244:245]
	v_pk_mul_f32 v[122:123], v[122:123], v[246:247]
	v_pk_mul_f32 v[104:105], v[104:105], v[244:245]
	v_pk_mul_f32 v[106:107], v[106:107], v[246:247]
	v_pk_mul_f32 v[88:89], v[88:89], v[244:245]
	v_pk_mul_f32 v[90:91], v[90:91], v[246:247]
	v_pk_mul_f32 v[72:73], v[72:73], v[244:245]
	v_pk_mul_f32 v[74:75], v[74:75], v[246:247]
	v_pk_mul_f32 v[56:57], v[56:57], v[244:245]
	v_pk_mul_f32 v[58:59], v[58:59], v[246:247]
	v_pk_mul_f32 v[40:41], v[40:41], v[244:245]
	v_pk_mul_f32 v[42:43], v[42:43], v[246:247]
	v_pk_mul_f32 v[24:25], v[24:25], v[244:245]
	v_pk_mul_f32 v[26:27], v[26:27], v[246:247]
	s_waitcnt lgkmcnt(0)
	v_pk_mul_f32 v[4:5], v[4:5], v[248:249]
	v_pk_mul_f32 v[6:7], v[6:7], v[250:251]
	v_pk_mul_f32 v[116:117], v[116:117], v[248:249]
	v_pk_mul_f32 v[118:119], v[118:119], v[250:251]
	v_pk_mul_f32 v[100:101], v[100:101], v[248:249]
	v_pk_mul_f32 v[102:103], v[102:103], v[250:251]
	v_pk_mul_f32 v[84:85], v[84:85], v[248:249]
	v_pk_mul_f32 v[86:87], v[86:87], v[250:251]
	v_pk_mul_f32 v[68:69], v[68:69], v[248:249]
	v_pk_mul_f32 v[70:71], v[70:71], v[250:251]
	v_pk_mul_f32 v[52:53], v[52:53], v[248:249]
	v_pk_mul_f32 v[54:55], v[54:55], v[250:251]
	v_pk_mul_f32 v[36:37], v[36:37], v[248:249]
	v_pk_mul_f32 v[38:39], v[38:39], v[250:251]
	v_pk_mul_f32 v[20:21], v[20:21], v[248:249]
	v_pk_mul_f32 v[22:23], v[22:23], v[250:251]
	s_branch .Lv2_back_h3
.Lv2_rare_h4:
	v_mov_b32_e32 v189, v188
	s_nop 1
	v_permlane32_swap_b32_e32 v188, v189
	v_max_f32_e32 v188, v188, v189
	v_mul_f32_e32 v189, v236, v188
	v_fma_f32 v188, v236, v188, -v237
	v_max_f32_e32 v189, v237, v189
	v_cmp_gt_f32_e32 vcc, v188, v220
	s_nop 1
	v_cndmask_b32_e32 v189, v237, v189, vcc
	v_sub_f32_e32 v188, v237, v189
	v_mul_f32_e32 v188, v221, v188
	v_exp_f32_e32 v254, v188
	v_mov_b32_e32 v237, v189
	v_mul_f32_e32 v255, v221, v189
	v_mul_f32_e32 v224, v224, v254
	s_and_saveexec_b64 vcc, s[0:1]
	ds_write_b32 v223, v254
	s_or_b64 exec, exec, vcc
	s_waitcnt lgkmcnt(0)
	v_add_u32_e32 v253, s78, v218
	ds_read_b128 v[244:247], v253 offset:96
	ds_read_b128 v[248:251], v253 offset:64
	s_waitcnt lgkmcnt(1)
	v_pk_mul_f32 v[16:17], v[16:17], v[244:245]
	v_pk_mul_f32 v[18:19], v[18:19], v[246:247]
	v_pk_mul_f32 v[128:129], v[128:129], v[244:245]
	v_pk_mul_f32 v[130:131], v[130:131], v[246:247]
	v_pk_mul_f32 v[112:113], v[112:113], v[244:245]
	v_pk_mul_f32 v[114:115], v[114:115], v[246:247]
	v_pk_mul_f32 v[96:97], v[96:97], v[244:245]
	v_pk_mul_f32 v[98:99], v[98:99], v[246:247]
	v_pk_mul_f32 v[80:81], v[80:81], v[244:245]
	v_pk_mul_f32 v[82:83], v[82:83], v[246:247]
	v_pk_mul_f32 v[64:65], v[64:65], v[244:245]
	v_pk_mul_f32 v[66:67], v[66:67], v[246:247]
	v_pk_mul_f32 v[48:49], v[48:49], v[244:245]
	v_pk_mul_f32 v[50:51], v[50:51], v[246:247]
	v_pk_mul_f32 v[32:33], v[32:33], v[244:245]
	v_pk_mul_f32 v[34:35], v[34:35], v[246:247]
	s_waitcnt lgkmcnt(0)
	v_pk_mul_f32 v[12:13], v[12:13], v[248:249]
	v_pk_mul_f32 v[14:15], v[14:15], v[250:251]
	v_pk_mul_f32 v[124:125], v[124:125], v[248:249]
	v_pk_mul_f32 v[126:127], v[126:127], v[250:251]
	v_pk_mul_f32 v[108:109], v[108:109], v[248:249]
	v_pk_mul_f32 v[110:111], v[110:111], v[250:251]
	v_pk_mul_f32 v[92:93], v[92:93], v[248:249]
	v_pk_mul_f32 v[94:95], v[94:95], v[250:251]
	v_pk_mul_f32 v[76:77], v[76:77], v[248:249]
	v_pk_mul_f32 v[78:79], v[78:79], v[250:251]
	v_pk_mul_f32 v[60:61], v[60:61], v[248:249]
	v_pk_mul_f32 v[62:63], v[62:63], v[250:251]
	v_pk_mul_f32 v[44:45], v[44:45], v[248:249]
	v_pk_mul_f32 v[46:47], v[46:47], v[250:251]
	v_pk_mul_f32 v[28:29], v[28:29], v[248:249]
	v_pk_mul_f32 v[30:31], v[30:31], v[250:251]
	ds_read_b128 v[244:247], v253 offset:32
	ds_read_b128 v[248:251], v253
	s_waitcnt lgkmcnt(1)
	v_pk_mul_f32 v[8:9], v[8:9], v[244:245]
	v_pk_mul_f32 v[10:11], v[10:11], v[246:247]
	v_pk_mul_f32 v[120:121], v[120:121], v[244:245]
	v_pk_mul_f32 v[122:123], v[122:123], v[246:247]
	v_pk_mul_f32 v[104:105], v[104:105], v[244:245]
	v_pk_mul_f32 v[106:107], v[106:107], v[246:247]
	v_pk_mul_f32 v[88:89], v[88:89], v[244:245]
	v_pk_mul_f32 v[90:91], v[90:91], v[246:247]
	v_pk_mul_f32 v[72:73], v[72:73], v[244:245]
	v_pk_mul_f32 v[74:75], v[74:75], v[246:247]
	v_pk_mul_f32 v[56:57], v[56:57], v[244:245]
	v_pk_mul_f32 v[58:59], v[58:59], v[246:247]
	v_pk_mul_f32 v[40:41], v[40:41], v[244:245]
	v_pk_mul_f32 v[42:43], v[42:43], v[246:247]
	v_pk_mul_f32 v[24:25], v[24:25], v[244:245]
	v_pk_mul_f32 v[26:27], v[26:27], v[246:247]
	s_waitcnt lgkmcnt(0)
	v_pk_mul_f32 v[4:5], v[4:5], v[248:249]
	v_pk_mul_f32 v[6:7], v[6:7], v[250:251]
	v_pk_mul_f32 v[116:117], v[116:117], v[248:249]
	v_pk_mul_f32 v[118:119], v[118:119], v[250:251]
	v_pk_mul_f32 v[100:101], v[100:101], v[248:249]
	v_pk_mul_f32 v[102:103], v[102:103], v[250:251]
	v_pk_mul_f32 v[84:85], v[84:85], v[248:249]
	v_pk_mul_f32 v[86:87], v[86:87], v[250:251]
	v_pk_mul_f32 v[68:69], v[68:69], v[248:249]
	v_pk_mul_f32 v[70:71], v[70:71], v[250:251]
	v_pk_mul_f32 v[52:53], v[52:53], v[248:249]
	v_pk_mul_f32 v[54:55], v[54:55], v[250:251]
	v_pk_mul_f32 v[36:37], v[36:37], v[248:249]
	v_pk_mul_f32 v[38:39], v[38:39], v[250:251]
	v_pk_mul_f32 v[20:21], v[20:21], v[248:249]
	v_pk_mul_f32 v[22:23], v[22:23], v[250:251]
	s_branch .Lv2_back_h4
.Lb4_loop:
	s_add_i32 s2, s79, -1
	s_min_u32 s85, s2, s84
	s_lshl_b32 s4, s85, 6
	s_cmp_lt_u32 s85, 4
	s_cselect_b64 s[2:3], -1, 0
	s_add_i32 s88, s4, 0xffffff00
	s_and_b64 s[86:87], s[2:3], exec
	s_cselect_b32 s4, s4, s88
	s_cselect_b32 s88, s17, s73
	s_cselect_b32 s89, s16, s72
	s_lshl_b64 s[86:87], s[4:5], 7
	s_add_u32 s86, s89, s86
	s_addc_u32 s87, s88, s87
	s_lshl_b32 s88, s85, 1
	s_mov_b32 s89, s5
	s_lshl_b64 s[88:89], s[88:89], 2
	s_add_u32 s85, s18, s88
	s_addc_u32 s90, s19, s89
	s_add_u32 s88, s74, s88
	s_addc_u32 s89, s75, s89
	s_add_u32 s88, s88, 0xffffffe0
	s_addc_u32 s89, s89, -1
	s_and_b64 s[2:3], s[2:3], exec
	s_cselect_b32 s3, s90, s89
	s_cselect_b32 s2, s85, s88
	s_waitcnt vmcnt(0) lgkmcnt(0)
	s_barrier
	s_setprio 0
	s_waitcnt lgkmcnt(2)
	v_mfma_f32_32x32x16_bf16 v[4:19], v[152:155], v[184:187], v[4:19]
	ds_read_b64_tr_b16 v[156:157], v222 offset:50176
	ds_read_b64_tr_b16 v[158:159], v222 offset:54272
	s_waitcnt lgkmcnt(2)
	v_mfma_f32_32x32x16_bf16 v[116:131], v[152:155], v[180:183], v[116:131]
	ds_read_b64_tr_b16 v[160:161], v222 offset:50688
	ds_read_b64_tr_b16 v[162:163], v222 offset:54784
	s_waitcnt lgkmcnt(2)
	v_mfma_f32_32x32x16_bf16 v[100:115], v[152:155], v[156:159], v[100:115]
	ds_read_b64_tr_b16 v[156:157], v222 offset:51200
	ds_read_b64_tr_b16 v[158:159], v222 offset:55296
	s_waitcnt lgkmcnt(2)
	v_mfma_f32_32x32x16_bf16 v[84:99], v[152:155], v[160:163], v[84:99]
	ds_read_b64_tr_b16 v[160:161], v222 offset:51712
	ds_read_b64_tr_b16 v[162:163], v222 offset:55808
	s_waitcnt lgkmcnt(2)
	v_mfma_f32_32x32x16_bf16 v[68:83], v[152:155], v[156:159], v[68:83]
	ds_read_b64_tr_b16 v[156:157], v222 offset:52224
	ds_read_b64_tr_b16 v[158:159], v222 offset:56320
	s_waitcnt lgkmcnt(2)
	v_mfma_f32_32x32x16_bf16 v[52:67], v[152:155], v[160:163], v[52:67]
	ds_read_b64_tr_b16 v[160:161], v222 offset:52736
	ds_read_b64_tr_b16 v[162:163], v222 offset:56832
	s_waitcnt lgkmcnt(2)
	v_mfma_f32_32x32x16_bf16 v[36:51], v[152:155], v[156:159], v[36:51]
	ds_read_b64_tr_b16 v[156:157], v222 offset:57344
	ds_read_b64_tr_b16 v[158:159], v222 offset:61440
	s_waitcnt lgkmcnt(2)
	v_mfma_f32_32x32x16_bf16 v[20:35], v[152:155], v[160:163], v[20:35]
	ds_read_b64_tr_b16 v[152:153], v222 offset:57856
	ds_read_b64_tr_b16 v[154:155], v222 offset:61952
	s_waitcnt lgkmcnt(2)
	v_mfma_f32_32x32x16_bf16 v[4:19], v[148:151], v[156:159], v[4:19]
	ds_read_b64_tr_b16 v[156:157], v222 offset:58368
	ds_read_b64_tr_b16 v[158:159], v222 offset:62464
	s_waitcnt lgkmcnt(2)
	v_mfma_f32_32x32x16_bf16 v[116:131], v[148:151], v[152:155], v[116:131]
	ds_read_b64_tr_b16 v[152:153], v222 offset:58880
	ds_read_b64_tr_b16 v[154:155], v222 offset:62976
	s_waitcnt lgkmcnt(2)
	v_mfma_f32_32x32x16_bf16 v[100:115], v[148:151], v[156:159], v[100:115]
	ds_read_b64_tr_b16 v[156:157], v222 offset:59392
	ds_read_b64_tr_b16 v[158:159], v222 offset:63488
	s_waitcnt lgkmcnt(2)
	v_mfma_f32_32x32x16_bf16 v[84:99], v[148:151], v[152:155], v[84:99]
	ds_read_b64_tr_b16 v[152:153], v222 offset:59904
	ds_read_b64_tr_b16 v[154:155], v222 offset:64000
	s_waitcnt lgkmcnt(2)
	v_mfma_f32_32x32x16_bf16 v[68:83], v[148:151], v[156:159], v[68:83]
	ds_read_b64_tr_b16 v[156:157], v222 offset:60416
	ds_read_b64_tr_b16 v[158:159], v222 offset:64512
	s_waitcnt lgkmcnt(2)
	v_mfma_f32_32x32x16_bf16 v[52:67], v[148:151], v[152:155], v[52:67]
	ds_read_b64_tr_b16 v[152:153], v222 offset:60928
	ds_read_b64_tr_b16 v[154:155], v222 offset:65024
	s_waitcnt lgkmcnt(2)
	v_mfma_f32_32x32x16_bf16 v[36:51], v[148:151], v[156:159], v[36:51]
	s_waitcnt lgkmcnt(0)
	v_mfma_f32_32x32x16_bf16 v[20:35], v[148:151], v[152:155], v[20:35]
.Lb4_mid:
	s_barrier
	s_setprio 1
	s_waitcnt vmcnt(0)
	global_load_dwordx2 v[208:209], v201, s[2:3]
	s_cselect_b32 s85, s21, s77
	s_cselect_b32 s88, s20, s76
	s_lshl_b64 s[2:3], s[4:5], 9
	s_add_u32 s2, s88, s2
	ds_read_b128 v[180:183], v225
	ds_read_b128 v[184:187], v226
	s_addc_u32 s3, s85, s3
	s_cmp_lg_u32 0, -1
	s_cselect_b32 s4, 0, 0
	s_add_i32 s85, s4, s80
	s_add_i32 s4, s4, s81
	s_addk_i32 s85, 0x4000
	s_add_i32 s88, s4, 0x10000
	s_waitcnt lgkmcnt(1)
	v_mfma_i32_32x32x32_i8 v[148:163], v[180:183], v[164:167], v[132:147]
	ds_read_b128 v[180:183], v227
	s_waitcnt lgkmcnt(1)
	v_mfma_i32_32x32x32_i8 v[148:163], v[184:187], v[168:171], v[148:163]
	ds_read_b128 v[188:191], v228
	s_waitcnt lgkmcnt(1)
	v_mfma_i32_32x32x32_i8 v[148:163], v[180:183], v[172:175], v[148:163]
	ds_read_b64_tr_b16 v[184:185], v3 offset:32768
	ds_read_b64_tr_b16 v[186:187], v3 offset:36864
	s_waitcnt lgkmcnt(2)
	v_mfma_i32_32x32x32_i8 v[148:163], v[188:191], v[176:179], v[148:163]
	ds_read_b64_tr_b16 v[180:181], v3 offset:33280
	ds_read_b64_tr_b16 v[182:183], v3 offset:37376
	s_nop 9
	v_max3_f32 v188, v148, v149, v150
	v_max3_f32 v189, v151, v152, v153
	v_max3_f32 v190, v154, v155, v156
	v_max3_f32 v191, v157, v158, v159
	v_max3_f32 v192, v160, v161, v162
	v_max3_f32 v188, v188, v189, v190
	v_max3_f32 v191, v191, v192, v163
	v_max_f32_e32 v188, v188, v191
	v_add_f32_e32 v188, 0xcb400000, v188
	v_fma_f32 v189, v206, v188, -v237
	v_cmp_gt_f32_e32 vcc, v189, v220
	s_cbranch_vccnz .Lb2_rare_h1

.Lb2_back_h2:
	v_mul_f32_e32 v189, v221, v207
	v_fma_f32 v190, s100, v189, v255
	v_fma_f32 v148, v148, v189, -v190
	v_fma_f32 v149, v149, v189, -v190
	v_exp_f32_e32 v148, v148
	v_fma_f32 v150, v150, v189, -v190
	v_exp_f32_e32 v149, v149
	v_fma_f32 v151, v151, v189, -v190
	v_exp_f32_e32 v150, v150
	v_fma_f32 v152, v152, v189, -v190
	v_exp_f32_e32 v151, v151
	v_fma_f32 v153, v153, v189, -v190
	v_exp_f32_e32 v152, v152
	v_fma_f32 v154, v154, v189, -v190
	v_exp_f32_e32 v153, v153
	v_fma_f32 v155, v155, v189, -v190
	v_exp_f32_e32 v154, v154
	v_fma_f32 v156, v156, v189, -v190
	v_exp_f32_e32 v155, v155
	v_fma_f32 v157, v157, v189, -v190
	v_exp_f32_e32 v156, v156
	v_fma_f32 v158, v158, v189, -v190
	v_exp_f32_e32 v157, v157
	v_fma_f32 v159, v159, v189, -v190
	v_exp_f32_e32 v158, v158
	v_fma_f32 v160, v160, v189, -v190
	v_exp_f32_e32 v159, v159
	v_fma_f32 v161, v161, v189, -v190
	v_exp_f32_e32 v160, v160
	v_fma_f32 v162, v162, v189, -v190
	v_exp_f32_e32 v161, v161
	v_fma_f32 v163, v163, v189, -v190
	v_exp_f32_e32 v162, v162
	v_exp_f32_e32 v163, v163
	v_add_f32_e32 v188, v148, v149
	v_add_f32_e32 v189, v150, v151
	v_add_f32_e32 v190, v152, v153
	v_add_f32_e32 v191, v154, v155
	v_add_f32_e32 v192, v156, v157
	v_add_f32_e32 v193, v158, v159
	v_add_f32_e32 v194, v160, v161
	v_add_f32_e32 v195, v162, v163
	v_add_f32_e32 v188, v188, v189
	v_add_f32_e32 v190, v190, v191
	v_add_f32_e32 v192, v192, v193
	v_add_f32_e32 v194, v194, v195
	v_add_f32_e32 v188, v188, v190
	v_add_f32_e32 v192, v192, v194
	v_add_f32_e32 v188, v188, v192
	v_add_f32_e32 v224, v224, v188
	v_cvt_pk_bf16_f32 v155, v154, v155
	v_cvt_pk_bf16_f32 v154, v152, v153
	v_cvt_pk_bf16_f32 v152, v148, v149
	v_cvt_pk_bf16_f32 v153, v150, v151
	v_cvt_pk_bf16_f32 v148, v156, v157
	v_cvt_pk_bf16_f32 v149, v158, v159
	v_cvt_pk_bf16_f32 v150, v160, v161
	v_cvt_pk_bf16_f32 v151, v162, v163
	s_min_u32 s85, s79, s84
	s_lshl_b32 s4, s85, 6
	s_cmp_lt_u32 s85, 4
	s_cselect_b64 s[2:3], -1, 0
	s_add_i32 s88, s4, 0xffffff00
	s_and_b64 s[86:87], s[2:3], exec
	s_cselect_b32 s4, s4, s88
	s_cselect_b32 s88, s17, s73
	s_cselect_b32 s89, s16, s72
	s_lshl_b64 s[86:87], s[4:5], 7
	s_add_u32 s86, s89, s86
	s_addc_u32 s87, s88, s87
	s_lshl_b32 s88, s85, 1
	s_mov_b32 s89, s5
	s_lshl_b64 s[88:89], s[88:89], 2
	s_add_u32 s85, s18, s88
	s_addc_u32 s90, s19, s89
	s_add_u32 s88, s74, s88
	s_addc_u32 s89, s75, s89
	s_add_u32 s88, s88, 0xffffffe0
	s_addc_u32 s89, s89, -1
	s_and_b64 s[2:3], s[2:3], exec
	s_waitcnt vmcnt(0)
	v_mov_b32_e32 v236, v209
	s_cselect_b32 s3, s90, s89
	s_cselect_b32 s2, s85, s88
	s_waitcnt vmcnt(0) lgkmcnt(0)
	s_barrier
	s_setprio 0
	s_waitcnt lgkmcnt(2)
	v_mfma_f32_32x32x16_bf16 v[4:19], v[152:155], v[184:187], v[4:19]
	ds_read_b64_tr_b16 v[156:157], v3 offset:50176
	ds_read_b64_tr_b16 v[158:159], v3 offset:54272
	s_waitcnt lgkmcnt(2)
	v_mfma_f32_32x32x16_bf16 v[116:131], v[152:155], v[180:183], v[116:131]
	ds_read_b64_tr_b16 v[160:161], v3 offset:50688
	ds_read_b64_tr_b16 v[162:163], v3 offset:54784
	s_waitcnt lgkmcnt(2)
	v_mfma_f32_32x32x16_bf16 v[100:115], v[152:155], v[156:159], v[100:115]
	ds_read_b64_tr_b16 v[156:157], v3 offset:51200
	ds_read_b64_tr_b16 v[158:159], v3 offset:55296
	s_waitcnt lgkmcnt(2)
	v_mfma_f32_32x32x16_bf16 v[84:99], v[152:155], v[160:163], v[84:99]
	ds_read_b64_tr_b16 v[160:161], v3 offset:51712
	ds_read_b64_tr_b16 v[162:163], v3 offset:55808
	s_waitcnt lgkmcnt(2)
	v_mfma_f32_32x32x16_bf16 v[68:83], v[152:155], v[156:159], v[68:83]
	ds_read_b64_tr_b16 v[156:157], v3 offset:52224
	ds_read_b64_tr_b16 v[158:159], v3 offset:56320
	s_waitcnt lgkmcnt(2)
	v_mfma_f32_32x32x16_bf16 v[52:67], v[152:155], v[160:163], v[52:67]
	ds_read_b64_tr_b16 v[160:161], v3 offset:52736
	ds_read_b64_tr_b16 v[162:163], v3 offset:56832
	s_waitcnt lgkmcnt(2)
	v_mfma_f32_32x32x16_bf16 v[36:51], v[152:155], v[156:159], v[36:51]
	ds_read_b64_tr_b16 v[156:157], v3 offset:57344
	ds_read_b64_tr_b16 v[158:159], v3 offset:61440
	s_waitcnt lgkmcnt(2)
	v_mfma_f32_32x32x16_bf16 v[20:35], v[152:155], v[160:163], v[20:35]
	ds_read_b64_tr_b16 v[152:153], v3 offset:57856
	ds_read_b64_tr_b16 v[154:155], v3 offset:61952
	s_waitcnt lgkmcnt(2)
	v_mfma_f32_32x32x16_bf16 v[4:19], v[148:151], v[156:159], v[4:19]
	ds_read_b64_tr_b16 v[156:157], v3 offset:58368
	ds_read_b64_tr_b16 v[158:159], v3 offset:62464
	s_waitcnt lgkmcnt(2)
	v_mfma_f32_32x32x16_bf16 v[116:131], v[148:151], v[152:155], v[116:131]
	ds_read_b64_tr_b16 v[152:153], v3 offset:58880
	ds_read_b64_tr_b16 v[154:155], v3 offset:62976
	s_waitcnt lgkmcnt(2)
	v_mfma_f32_32x32x16_bf16 v[100:115], v[148:151], v[156:159], v[100:115]
	ds_read_b64_tr_b16 v[156:157], v3 offset:59392
	ds_read_b64_tr_b16 v[158:159], v3 offset:63488
	s_waitcnt lgkmcnt(2)
	v_mfma_f32_32x32x16_bf16 v[84:99], v[148:151], v[152:155], v[84:99]
	ds_read_b64_tr_b16 v[152:153], v3 offset:59904
	ds_read_b64_tr_b16 v[154:155], v3 offset:64000
	s_waitcnt lgkmcnt(2)
	v_mfma_f32_32x32x16_bf16 v[68:83], v[148:151], v[156:159], v[68:83]
	ds_read_b64_tr_b16 v[156:157], v3 offset:60416
	ds_read_b64_tr_b16 v[158:159], v3 offset:64512
	s_waitcnt lgkmcnt(2)
	v_mfma_f32_32x32x16_bf16 v[52:67], v[148:151], v[152:155], v[52:67]
	ds_read_b64_tr_b16 v[152:153], v3 offset:60928
	ds_read_b64_tr_b16 v[154:155], v3 offset:65024
	s_waitcnt lgkmcnt(2)
	v_mfma_f32_32x32x16_bf16 v[36:51], v[148:151], v[156:159], v[36:51]
	s_waitcnt lgkmcnt(0)
	v_mfma_f32_32x32x16_bf16 v[20:35], v[148:151], v[152:155], v[20:35]
	s_barrier
	s_setprio 1
	global_load_dwordx2 v[206:207], v201, s[2:3]
	ds_read_b128 v[180:183], v225 offset:16384
	ds_read_b128 v[184:187], v226 offset:16384
	s_cselect_b32 s85, s21, s77
	s_cselect_b32 s88, s20, s76
	s_lshl_b64 s[2:3], s[4:5], 9
	s_add_u32 s2, s88, s2
	s_addc_u32 s3, s85, s3
	s_waitcnt lgkmcnt(1)
	v_mfma_i32_32x32x32_i8 v[148:163], v[180:183], v[164:167], v[132:147]
	ds_read_b128 v[180:183], v227 offset:16384
	s_waitcnt lgkmcnt(1)
	v_mfma_i32_32x32x32_i8 v[148:163], v[184:187], v[168:171], v[148:163]
	ds_read_b128 v[188:191], v228 offset:16384
	s_waitcnt lgkmcnt(1)
	v_mfma_i32_32x32x32_i8 v[148:163], v[180:183], v[172:175], v[148:163]
	ds_read_b64_tr_b16 v[184:185], v222 offset:32768
	ds_read_b64_tr_b16 v[186:187], v222 offset:36864
	s_waitcnt lgkmcnt(2)
	v_mfma_i32_32x32x32_i8 v[148:163], v[188:191], v[176:179], v[148:163]
	ds_read_b64_tr_b16 v[180:181], v222 offset:33280
	ds_read_b64_tr_b16 v[182:183], v222 offset:37376
	s_nop 9
	s_mov_b32 s90, s94
	v_max3_f32 v188, v148, v149, v150
	v_max3_f32 v189, v151, v152, v153
	v_max3_f32 v190, v154, v155, v156
	v_max3_f32 v191, v157, v158, v159
	v_max3_f32 v192, v160, v161, v162
	v_max3_f32 v188, v188, v189, v190
	v_max3_f32 v191, v191, v192, v163
	v_max_f32_e32 v188, v188, v191
	v_add_f32_e32 v188, 0xcb400000, v188
	v_fma_f32 v189, v208, v188, -v237
	v_cmp_gt_f32_e32 vcc, v189, v220
	s_cbranch_vccnz .Lb2_rare_h3

; __device__ __forceinline__ void attn_unit256q(const bf16* __restrict__ Qb, const unsigned char* __restrict__ Kc, const unsigned char* __restrict__ Kl, const float* __restrict__ Sc, const float* __restrict__ Sl, ...
;     ...
;   for (int j = 0; j < NT; j += 2) {
;     A5_TILE(0, 0, KBUF, VBUF, j);
;     A5_TILE(KBUF, VBUF, 0, 0, j + 1);
;   }
.Lb2_back_h4:
	v_mul_f32_e32 v189, v221, v236
	v_fma_f32 v190, s100, v189, v255
	v_fma_f32 v148, v148, v189, -v190
	v_fma_f32 v149, v149, v189, -v190
	v_exp_f32_e32 v148, v148
	v_fma_f32 v150, v150, v189, -v190
	v_exp_f32_e32 v149, v149
	v_fma_f32 v151, v151, v189, -v190
	v_exp_f32_e32 v150, v150
	v_fma_f32 v152, v152, v189, -v190
	v_exp_f32_e32 v151, v151
	v_fma_f32 v153, v153, v189, -v190
	v_exp_f32_e32 v152, v152
	v_fma_f32 v154, v154, v189, -v190
	v_exp_f32_e32 v153, v153
	v_fma_f32 v155, v155, v189, -v190
	v_exp_f32_e32 v154, v154
	v_fma_f32 v156, v156, v189, -v190
	v_exp_f32_e32 v155, v155
	v_fma_f32 v157, v157, v189, -v190
	v_exp_f32_e32 v156, v156
	v_fma_f32 v158, v158, v189, -v190
	v_exp_f32_e32 v157, v157
	v_fma_f32 v159, v159, v189, -v190
	v_exp_f32_e32 v158, v158
	v_fma_f32 v160, v160, v189, -v190
	v_exp_f32_e32 v159, v159
	v_fma_f32 v161, v161, v189, -v190
	v_exp_f32_e32 v160, v160
	v_fma_f32 v162, v162, v189, -v190
	v_exp_f32_e32 v161, v161
	v_fma_f32 v163, v163, v189, -v190
	v_exp_f32_e32 v162, v162
	v_exp_f32_e32 v163, v163
	v_add_f32_e32 v188, v148, v149
	v_add_f32_e32 v189, v150, v151
	v_add_f32_e32 v190, v152, v153
	v_add_f32_e32 v191, v154, v155
	v_add_f32_e32 v192, v156, v157
	v_add_f32_e32 v193, v158, v159
	v_add_f32_e32 v194, v160, v161
	v_add_f32_e32 v195, v162, v163
	v_add_f32_e32 v188, v188, v189
	v_add_f32_e32 v190, v190, v191
	v_add_f32_e32 v192, v192, v193
	v_add_f32_e32 v194, v194, v195
	v_add_f32_e32 v188, v188, v190
	v_add_f32_e32 v192, v192, v194
	v_add_f32_e32 v188, v188, v192
	v_add_f32_e32 v224, v224, v188
	v_cvt_pk_bf16_f32 v155, v154, v155
	v_cvt_pk_bf16_f32 v154, v152, v153
	v_cvt_pk_bf16_f32 v152, v148, v149
	v_cvt_pk_bf16_f32 v153, v150, v151
	v_cvt_pk_bf16_f32 v148, v156, v157
	v_cvt_pk_bf16_f32 v149, v158, v159
	v_cvt_pk_bf16_f32 v150, v160, v161
	v_cvt_pk_bf16_f32 v151, v162, v163
	s_add_i32 s2, s79, 2
	s_cmp_ge_u32 s79, s70
	s_cbranch_scc1 .Lb4_exit
	s_mov_b32 s79, s2
	s_branch .Lb4_loop

.Lb4_entry:
	s_add_i32 s2, s79, -1
	s_min_u32 s85, s2, s84
	s_lshl_b32 s4, s85, 6
	s_cmp_lt_u32 s85, 4
	s_cselect_b64 s[2:3], -1, 0
	s_add_i32 s88, s4, 0xffffff00
	s_and_b64 s[86:87], s[2:3], exec
	s_cselect_b32 s4, s4, s88
	s_cselect_b32 s88, s17, s73
	s_cselect_b32 s89, s16, s72
	s_lshl_b64 s[86:87], s[4:5], 7
	s_add_u32 s86, s89, s86
	s_addc_u32 s87, s88, s87
	s_lshl_b32 s88, s85, 1
	s_mov_b32 s89, s5
	s_lshl_b64 s[88:89], s[88:89], 2
	s_add_u32 s85, s18, s88
	s_addc_u32 s90, s19, s89
	s_add_u32 s88, s74, s88
	s_addc_u32 s89, s75, s89
	s_add_u32 s88, s88, 0xffffffe0
	s_addc_u32 s89, s89, -1
	s_and_b64 s[2:3], s[2:3], exec
	s_cselect_b32 s3, s90, s89
	s_cselect_b32 s2, s85, s88
	s_waitcnt vmcnt(0) lgkmcnt(0)
	s_barrier
	s_branch .Lb4_mid
.Lb4_exit:
	s_setprio 0
	s_waitcnt lgkmcnt(2)
	v_mfma_f32_32x32x16_bf16 v[4:19], v[152:155], v[184:187], v[4:19]
	ds_read_b64_tr_b16 v[156:157], v222 offset:50176
	ds_read_b64_tr_b16 v[158:159], v222 offset:54272
	s_waitcnt lgkmcnt(2)
	v_mfma_f32_32x32x16_bf16 v[116:131], v[152:155], v[180:183], v[116:131]
	ds_read_b64_tr_b16 v[160:161], v222 offset:50688
	ds_read_b64_tr_b16 v[162:163], v222 offset:54784
	s_waitcnt lgkmcnt(2)
	v_mfma_f32_32x32x16_bf16 v[100:115], v[152:155], v[156:159], v[100:115]
	ds_read_b64_tr_b16 v[156:157], v222 offset:51200
	ds_read_b64_tr_b16 v[158:159], v222 offset:55296
	s_waitcnt lgkmcnt(2)
	v_mfma_f32_32x32x16_bf16 v[84:99], v[152:155], v[160:163], v[84:99]
	ds_read_b64_tr_b16 v[160:161], v222 offset:51712
	ds_read_b64_tr_b16 v[162:163], v222 offset:55808
	s_waitcnt lgkmcnt(2)
	v_mfma_f32_32x32x16_bf16 v[68:83], v[152:155], v[156:159], v[68:83]
	ds_read_b64_tr_b16 v[156:157], v222 offset:52224
	ds_read_b64_tr_b16 v[158:159], v222 offset:56320
	s_waitcnt lgkmcnt(2)
	v_mfma_f32_32x32x16_bf16 v[52:67], v[152:155], v[160:163], v[52:67]
	ds_read_b64_tr_b16 v[160:161], v222 offset:52736
	ds_read_b64_tr_b16 v[162:163], v222 offset:56832
	s_waitcnt lgkmcnt(2)
	v_mfma_f32_32x32x16_bf16 v[36:51], v[152:155], v[156:159], v[36:51]
	ds_read_b64_tr_b16 v[156:157], v222 offset:57344
	ds_read_b64_tr_b16 v[158:159], v222 offset:61440
	s_waitcnt lgkmcnt(2)
	v_mfma_f32_32x32x16_bf16 v[20:35], v[152:155], v[160:163], v[20:35]
	ds_read_b64_tr_b16 v[152:153], v222 offset:57856
	ds_read_b64_tr_b16 v[154:155], v222 offset:61952
	s_waitcnt lgkmcnt(2)
	v_mfma_f32_32x32x16_bf16 v[4:19], v[148:151], v[156:159], v[4:19]
	ds_read_b64_tr_b16 v[156:157], v222 offset:58368
	ds_read_b64_tr_b16 v[158:159], v222 offset:62464
	s_waitcnt lgkmcnt(2)
	v_mfma_f32_32x32x16_bf16 v[116:131], v[148:151], v[152:155], v[116:131]
	ds_read_b64_tr_b16 v[152:153], v222 offset:58880
	ds_read_b64_tr_b16 v[154:155], v222 offset:62976
	s_waitcnt lgkmcnt(2)
	v_mfma_f32_32x32x16_bf16 v[100:115], v[148:151], v[156:159], v[100:115]
	ds_read_b64_tr_b16 v[156:157], v222 offset:59392
	ds_read_b64_tr_b16 v[158:159], v222 offset:63488
	s_waitcnt lgkmcnt(2)
	v_mfma_f32_32x32x16_bf16 v[84:99], v[148:151], v[152:155], v[84:99]
	ds_read_b64_tr_b16 v[152:153], v222 offset:59904
	ds_read_b64_tr_b16 v[154:155], v222 offset:64000
	s_waitcnt lgkmcnt(2)
	v_mfma_f32_32x32x16_bf16 v[68:83], v[148:151], v[156:159], v[68:83]
	ds_read_b64_tr_b16 v[156:157], v222 offset:60416
	ds_read_b64_tr_b16 v[158:159], v222 offset:64512
	s_waitcnt lgkmcnt(2)
	v_mfma_f32_32x32x16_bf16 v[52:67], v[148:151], v[152:155], v[52:67]
	ds_read_b64_tr_b16 v[152:153], v222 offset:60928
	ds_read_b64_tr_b16 v[154:155], v222 offset:65024
	s_waitcnt lgkmcnt(2)
	v_mfma_f32_32x32x16_bf16 v[36:51], v[148:151], v[156:159], v[36:51]
	s_waitcnt lgkmcnt(0)
	v_mfma_f32_32x32x16_bf16 v[20:35], v[148:151], v[152:155], v[20:35]
	s_branch .LBB0_557
